# softmax max-subtraction folded into the QK^T MFMA accumulator init (MLA, SWA, NSA window attention loops): 32 fewer VALU per 64-key tile
# speedup vs baseline: 1.0174x; 1.0124x over previous
.LBB0_1198:
	s_abs_i32 s8, s51
	s_mul_hi_u32 s9, s8, s30
	s_mul_i32 s10, s9, s29
	s_ashr_i32 s2, s51, 31
	s_sub_i32 s8, s8, s10
	s_xor_b32 s2, s2, s26
	s_add_i32 s10, s9, 1
	s_sub_i32 s11, s8, s29
	s_cmp_ge_u32 s8, s29
	s_cselect_b32 s9, s10, s9
	s_cselect_b32 s8, s11, s8
	s_add_i32 s10, s9, 1
	s_cmp_ge_u32 s8, s29
	s_cselect_b32 s8, s10, s9
	s_xor_b32 s8, s8, s2
	s_sub_i32 s2, s8, s2
	s_mul_i32 s8, s2, s42
	s_sub_i32 s24, s51, s8
	s_ashr_i32 s25, s24, 31
	s_lshr_b32 s8, s25, 26
	s_add_i32 s8, s24, s8
	s_ashr_i32 s9, s8, 6
	s_and_b32 s10, s8, 0xffffffc0
	s_not_b32 s52, s9
	s_sub_i32 s8, s24, s10
	s_and_b32 s11, s2, 1
	s_add_i32 s52, s27, s52
	s_cmp_eq_u32 s11, 0
	s_cselect_b32 s9, s9, s52
	s_mul_i32 s2, s2, s27
	s_add_i32 s9, s9, s2
	s_lshl_b32 s2, s9, 8
	s_sub_i32 s11, s28, s2
	s_add_i32 s52, s11, 0xf00
	s_ashr_i32 s9, s8, 31
	s_mul_i32 s58, s8, 0x180000
	s_mul_hi_i32 s53, s8, 0x180000
	s_add_u32 s54, s4, s58
	s_addc_u32 s55, s5, s53
	v_or_b32_e32 v1, s52, v179
	v_mov_b64_e32 v[2:3], s[54:55]
	v_mad_i64_i32 v[2:3], s[54:55], v1, s31, v[2:3]
	v_lshl_add_u64 v[2:3], v[2:3], 0, v[166:167]
	v_mov_b32_e32 v1, v178
	global_load_dwordx4 v[118:121], v[2:3], off
	global_load_dwordx4 v[122:125], v[2:3], off offset:32
	global_load_dwordx4 v[126:129], v[2:3], off offset:64
	global_load_dwordx4 v[130:133], v[2:3], off offset:96
	global_load_dwordx4 v[134:137], v[2:3], off offset:128
	global_load_dwordx4 v[138:141], v[2:3], off offset:160
	global_load_dwordx4 v[142:145], v[2:3], off offset:192
	global_load_dwordx4 v[146:149], v[2:3], off offset:224
	global_load_dwordx4 v[150:153], v[2:3], off offset:256
	global_load_dwordx4 v[154:157], v[2:3], off offset:288
	global_load_dwordx4 v[158:161], v[2:3], off offset:320
	global_load_dwordx4 v[162:165], v[2:3], off offset:352
	s_lshl_b64 s[56:57], s[8:9], 20
	v_add_u32_e32 v185, s70, v1
	v_ashrrev_i32_e32 v4, 31, v185
	v_lshrrev_b32_e32 v4, 28, v4
	s_add_u32 s54, s6, s58
	v_lshlrev_b32_e32 v168, 3, v185
	v_add_u32_e32 v5, v185, v4
	s_addc_u32 s55, s7, s53
	v_ashrrev_i32_e32 v169, 31, v168
	v_ashrrev_i32_e32 v4, 4, v5
	v_and_b32_e32 v5, 0x1ffffff0, v5
	v_lshl_add_u64 v[2:3], v[168:169], 1, s[54:55]
	v_sub_u32_e32 v5, v185, v5
	s_add_u32 s56, s12, s56
	v_lshlrev_b32_e32 v170, 3, v5
	v_ashrrev_i32_e32 v5, 31, v4
	v_add_co_u32_e32 v8, vcc, s34, v2
	s_addc_u32 s57, s13, s57
	v_lshlrev_b64 v[172:173], 8, v[4:5]
	v_addc_co_u32_e32 v9, vcc, 0, v3, vcc
	v_lshl_add_u64 v[6:7], s[56:57], 0, v[172:173]
	v_ashrrev_i32_e32 v171, 31, v170
	global_load_dwordx4 v[98:101], v[2:3], off
	v_add_co_u32_e32 v2, vcc, s35, v2
	v_lshl_add_u64 v[6:7], v[170:171], 1, v[6:7]
	s_nop 0
	v_addc_co_u32_e32 v3, vcc, 0, v3, vcc
	global_load_dwordx4 v[102:105], v[8:9], off
	global_load_dwordx4 v[106:109], v[2:3], off
	global_load_dwordx4 v[110:113], v[6:7], off
	v_add_co_u32_e32 v2, vcc, s34, v6
	s_sub_i32 s2, 0x103f, s2
	s_nop 0
	v_addc_co_u32_e32 v3, vcc, 0, v7, vcc
	global_load_dwordx4 v[114:117], v[2:3], off
	s_ashr_i32 s9, s2, 31
	s_lshr_b32 s9, s9, 26
	s_add_i32 s2, s2, s9
	s_ashr_i32 s9, s2, 6
	s_add_i32 s2, s11, 0xf1f
	s_ashr_i32 s11, s2, 31
	s_lshr_b32 s11, s11, 26
	s_add_i32 s2, s2, s11
	s_ashr_i32 s2, s2, 6
	s_add_i32 s2, s2, 1
	s_min_i32 s2, s2, s9
	v_mul_hi_i32 v2, v185, s36
	v_add_u32_e32 v188, 0x200, v185
	v_add_u32_e32 v187, 0x400, v185
	s_cmp_lt_i32 s2, 1
	v_mul_lo_u32 v183, v4, s39
	s_mul_hi_i32 s53, s10, 0x180000
	s_mul_i32 s54, s10, 0x180000
	v_lshrrev_b32_e32 v191, 31, v2
	v_ashrrev_i32_e32 v192, 2, v2
	v_mul_hi_i32 v190, v188, s36
	v_mul_hi_i32 v189, v187, s36
	v_lshlrev_b32_e32 v184, 1, v170
	s_waitcnt vmcnt(63) expcnt(7) lgkmcnt(15)
	s_barrier
	s_cbranch_scc1 .LBB0_1208
	v_bfe_u32 v2, v1, 5, 1
	v_and_b32_e32 v3, 31, v1
	s_lshl_b64 s[56:57], s[24:25], 20
	v_or_b32_e32 v193, s52, v3
	v_lshlrev_b32_e32 v194, 2, v2
	v_lshrrev_b32_e32 v4, 2, v1
	v_and_b32_e32 v16, 16, v1
	v_lshlrev_b32_e32 v1, 2, v1
	v_mul_u32_u24_e32 v18, 0xc8, v3
	v_lshlrev_b32_e32 v202, 4, v2
	v_lshl_add_u64 v[2:3], s[56:57], 0, v[172:173]
	s_ashr_i32 s11, s10, 31
	v_and_b32_e32 v17, 12, v1
	v_add_u32_e32 v1, v192, v191
	v_lshl_add_u64 v[2:3], v[170:171], 1, v[2:3]
	s_lshl_b64 s[56:57], s[10:11], 20
	v_mul_lo_u32 v5, v1, s37
	v_mul_lo_u32 v195, v1, s38
	v_mov_b32_e32 v1, s57
	v_subrev_co_u32_e32 v2, vcc, s56, v2
	v_lshrrev_b32_e32 v6, 31, v190
	s_nop 0
	v_subb_co_u32_e32 v3, vcc, v3, v1, vcc
	v_lshl_add_u64 v[174:175], s[16:17], 0, v[2:3]
	v_lshlrev_b64 v[2:3], 1, v[168:169]
	v_ashrrev_i32_e32 v7, 2, v190
	v_lshrrev_b32_e32 v8, 31, v189
	v_ashrrev_i32_e32 v9, 2, v189
	v_mad_i64_i32 v[2:3], s[56:57], s24, v181, v[2:3]
	v_add_u32_e32 v6, v7, v6
	v_add_u32_e32 v8, v9, v8
	v_mov_b32_e32 v1, s53
	v_subrev_co_u32_e32 v2, vcc, s54, v2
	v_and_or_b32 v4, v4, 3, v194
	v_mul_lo_u32 v7, v6, s37
	v_mul_lo_u32 v9, v8, s37
	v_subb_co_u32_e32 v3, vcc, v3, v1, vcc
	v_mov_b32_e32 v14, v0
	v_mov_b32_e32 v15, v0
	v_add_lshl_u32 v196, v5, v185, 4
	v_mul_lo_u32 v197, v6, s38
	v_add_lshl_u32 v198, v7, v188, 4
	v_mul_lo_u32 v199, v8, s38
	v_add_lshl_u32 v200, v9, v187, 4
	v_mul_u32_u24_e32 v201, 0x140, v4
	v_lshl_add_u64 v[176:177], s[20:21], 0, v[2:3]
	v_mov_b32_e32 v1, v0
	v_mov_b32_e32 v2, v0
	v_mov_b32_e32 v3, v0
	v_mov_b32_e32 v4, v0
	v_mov_b32_e32 v5, v0
	v_mov_b32_e32 v6, v0
	v_mov_b32_e32 v7, v0
	v_mov_b32_e32 v8, v0
	v_mov_b32_e32 v9, v0
	v_mov_b32_e32 v10, v0
	v_mov_b32_e32 v11, v0
	v_mov_b32_e32 v12, v0
	v_mov_b32_e32 v13, v0
	v_lshlrev_b32_e32 v203, 1, v18
	v_mov_b64_e32 v[48:49], v[14:15]
	v_mov_b64_e32 v[64:65], v[14:15]
	v_mov_b64_e32 v[32:33], v[14:15]
	v_lshlrev_b32_e32 v204, 1, v16
	v_lshlrev_b32_e32 v205, 1, v17
	v_mov_b64_e32 v[46:47], v[12:13]
	v_mov_b64_e32 v[44:45], v[10:11]
	v_mov_b64_e32 v[42:43], v[8:9]
	v_mov_b64_e32 v[40:41], v[6:7]
	v_mov_b64_e32 v[38:39], v[4:5]
	v_mov_b64_e32 v[36:37], v[2:3]
	v_mov_b64_e32 v[34:35], v[0:1]
	v_mov_b64_e32 v[62:63], v[12:13]
	v_mov_b64_e32 v[60:61], v[10:11]
	v_mov_b64_e32 v[58:59], v[8:9]
	v_mov_b64_e32 v[56:57], v[6:7]
	v_mov_b64_e32 v[54:55], v[4:5]
	v_mov_b64_e32 v[52:53], v[2:3]
	v_mov_b64_e32 v[50:51], v[0:1]
	v_mov_b64_e32 v[30:31], v[12:13]
	v_mov_b64_e32 v[28:29], v[10:11]
	v_mov_b64_e32 v[26:27], v[8:9]
	v_mov_b64_e32 v[24:25], v[6:7]
	v_mov_b64_e32 v[22:23], v[4:5]
	v_mov_b64_e32 v[20:21], v[2:3]
	v_mov_b64_e32 v[18:19], v[0:1]
	v_mov_b64_e32 v[16:17], v[14:15]
	s_mov_b32 s11, 0
	v_mov_b32_e32 v186, 0
	v_mov_b32_e32 v206, 0xf149f2ca
	v_mov_b32_e32 v232, 0
	v_mov_b32_e32 v233, 0
	v_mov_b32_e32 v234, 0
	v_mov_b32_e32 v235, 0
	v_mov_b32_e32 v236, 0
	v_mov_b32_e32 v237, 0
	v_mov_b32_e32 v238, 0
	v_mov_b32_e32 v239, 0
	v_mov_b32_e32 v240, 0
	v_mov_b32_e32 v241, 0
	v_mov_b32_e32 v242, 0
	v_mov_b32_e32 v243, 0
	v_mov_b32_e32 v244, 0
	v_mov_b32_e32 v245, 0
	v_mov_b32_e32 v246, 0
	v_mov_b32_e32 v247, 0
	v_mov_b32_e32 v248, 0
	v_mov_b32_e32 v249, v206
	s_mov_b32 s55, 63
	v_mov_b64_e32 v[14:15], v[12:13]
	v_mov_b64_e32 v[12:13], v[10:11]
	v_mov_b64_e32 v[10:11], v[8:9]
	v_mov_b64_e32 v[8:9], v[6:7]
	v_mov_b64_e32 v[6:7], v[4:5]
	v_mov_b64_e32 v[4:5], v[2:3]
	v_mov_b64_e32 v[2:3], v[0:1]
	s_branch .LBB0_1201
.LBB0_1200:
	v_exp_f32_e32 v207, v82
	v_exp_f32_e32 v208, v83
	v_exp_f32_e32 v209, v84
	v_add_u32_e32 v1, s56, v201
	v_exp_f32_e32 v211, v86
	v_add3_u32 v1, v1, v204, v205
	v_exp_f32_e32 v224, v88
	v_exp_f32_e32 v226, v87
	v_exp_f32_e32 v225, v89
	v_exp_f32_e32 v227, v85
	ds_read_b64_tr_b16 v[86:87], v1 offset:25600
	ds_read_b64_tr_b16 v[88:89], v1 offset:28160
	v_cvt_pk_bf16_f32 v84, v211, v226
	v_cvt_pk_bf16_f32 v85, v224, v225
	v_cvt_pk_bf16_f32 v83, v209, v227
	v_cvt_pk_bf16_f32 v82, v207, v208
	ds_read_b64_tr_b16 v[212:213], v1 offset:25664
	ds_read_b64_tr_b16 v[216:217], v1 offset:25728
	ds_read_b64_tr_b16 v[220:221], v1 offset:25792
	ds_read_b64_tr_b16 v[214:215], v1 offset:28224
	ds_read_b64_tr_b16 v[218:219], v1 offset:28288
	ds_read_b64_tr_b16 v[222:223], v1 offset:28352
	s_waitcnt lgkmcnt(6)
	v_mfma_f32_32x32x16_bf16 v[50:65], v[86:89], v[82:85], v[50:65]
	v_exp_f32_e32 v228, v90
	v_exp_f32_e32 v229, v91
	v_exp_f32_e32 v230, v92
	v_exp_f32_e32 v231, v94
	s_waitcnt lgkmcnt(1)
	v_mfma_f32_32x32x16_bf16 v[18:33], v[216:219], v[82:85], v[18:33]
	v_exp_f32_e32 v216, v96
	v_exp_f32_e32 v217, v97
	v_exp_f32_e32 v218, v95
	v_exp_f32_e32 v219, v93
	ds_read_b64_tr_b16 v[86:87], v1 offset:30720
	ds_read_b64_tr_b16 v[88:89], v1 offset:33280
	v_add_f32_e32 v207, 0, v207
	v_mfma_f32_32x32x16_bf16 v[34:49], v[212:215], v[82:85], v[34:49]
	ds_read_b64_tr_b16 v[90:91], v1 offset:30784
	ds_read_b64_tr_b16 v[94:95], v1 offset:30848
	ds_read_b64_tr_b16 v[212:213], v1 offset:30912
	ds_read_b64_tr_b16 v[92:93], v1 offset:33344
	ds_read_b64_tr_b16 v[96:97], v1 offset:33408
	ds_read_b64_tr_b16 v[214:215], v1 offset:33472
	s_add_i32 s55, s55, 64
	v_lshl_add_u64 v[174:175], v[174:175], 0, s[14:15]
	s_cmp_eq_u32 s2, s11
	v_lshl_add_u64 v[176:177], v[176:177], 0, s[18:19]
	s_waitcnt lgkmcnt(8)
	v_mfma_f32_32x32x16_bf16 v[2:17], v[220:223], v[82:85], v[2:17]
	v_cvt_pk_bf16_f32 v85, v216, v217
	v_cvt_pk_bf16_f32 v84, v231, v218
	v_cvt_pk_bf16_f32 v83, v230, v219
	v_cvt_pk_bf16_f32 v82, v228, v229
	s_waitcnt lgkmcnt(6)
	s_nop 0
	v_mfma_f32_32x32x16_bf16 v[50:65], v[86:89], v[82:85], v[50:65]
	v_add_f32_e32 v86, v208, v207
	v_add_f32_e32 v86, v209, v86
	v_exp_f32_e32 v208, v66
	v_add_f32_e32 v86, v227, v86
	v_exp_f32_e32 v209, v67
	v_add_f32_e32 v86, v211, v86
	v_exp_f32_e32 v211, v68
	v_exp_f32_e32 v220, v70
	s_waitcnt lgkmcnt(1)
	v_mfma_f32_32x32x16_bf16 v[18:33], v[94:97], v[82:85], v[18:33]
	v_exp_f32_e32 v94, v72
	v_exp_f32_e32 v95, v73
	v_exp_f32_e32 v96, v71
	v_exp_f32_e32 v97, v69
	ds_read_b64_tr_b16 v[70:71], v1 offset:35840
	ds_read_b64_tr_b16 v[72:73], v1 offset:38400
	v_add_f32_e32 v207, v226, v86
	v_cvt_pk_bf16_f32 v69, v94, v95
	v_cvt_pk_bf16_f32 v68, v220, v96
	v_cvt_pk_bf16_f32 v67, v211, v97
	v_cvt_pk_bf16_f32 v66, v208, v209
	v_mfma_f32_32x32x16_bf16 v[34:49], v[90:93], v[82:85], v[34:49]
	s_waitcnt lgkmcnt(0)
	v_mfma_f32_32x32x16_bf16 v[50:65], v[70:73], v[66:69], v[50:65]
	v_add_f32_e32 v70, v224, v207
	v_add_f32_e32 v70, v225, v70
	v_add_f32_e32 v70, v228, v70
	v_add_f32_e32 v70, v229, v70
	v_add_f32_e32 v207, v230, v70
	v_mfma_f32_32x32x16_bf16 v[2:17], v[212:215], v[82:85], v[2:17]
	ds_read_b64_tr_b16 v[82:83], v1 offset:35904
	ds_read_b64_tr_b16 v[86:87], v1 offset:35968
	ds_read_b64_tr_b16 v[90:91], v1 offset:36032
	ds_read_b64_tr_b16 v[84:85], v1 offset:38464
	ds_read_b64_tr_b16 v[88:89], v1 offset:38528
	ds_read_b64_tr_b16 v[92:93], v1 offset:38592
	v_exp_f32_e32 v212, v74
	v_exp_f32_e32 v213, v75
	v_exp_f32_e32 v214, v76
	v_exp_f32_e32 v215, v78
	s_waitcnt lgkmcnt(1)
	v_mfma_f32_32x32x16_bf16 v[18:33], v[86:89], v[66:69], v[18:33]
	v_exp_f32_e32 v86, v80
	v_exp_f32_e32 v87, v81
	v_exp_f32_e32 v88, v79
	v_exp_f32_e32 v89, v77
	ds_read_b64_tr_b16 v[70:71], v1 offset:40960
	ds_read_b64_tr_b16 v[72:73], v1 offset:43520
	v_mfma_f32_32x32x16_bf16 v[34:49], v[82:85], v[66:69], v[34:49]
	ds_read_b64_tr_b16 v[74:75], v1 offset:41024
	ds_read_b64_tr_b16 v[78:79], v1 offset:41088
	ds_read_b64_tr_b16 v[82:83], v1 offset:41152
	ds_read_b64_tr_b16 v[76:77], v1 offset:43584
	ds_read_b64_tr_b16 v[80:81], v1 offset:43648
	ds_read_b64_tr_b16 v[84:85], v1 offset:43712
	v_add_f32_e32 v1, v219, v207
	v_add_f32_e32 v1, v231, v1
	v_add_f32_e32 v1, v218, v1
	v_add_f32_e32 v1, v216, v1
	v_add_f32_e32 v1, v217, v1
	v_add_f32_e32 v1, v208, v1
	s_waitcnt lgkmcnt(8)
	v_mfma_f32_32x32x16_bf16 v[2:17], v[90:93], v[66:69], v[2:17]
	v_add_f32_e32 v1, v209, v1
	v_add_f32_e32 v1, v211, v1
	v_add_f32_e32 v1, v97, v1
	v_add_f32_e32 v1, v220, v1
	v_add_f32_e32 v1, v96, v1
	v_add_f32_e32 v1, v94, v1
	v_add_f32_e32 v1, v95, v1
	v_cvt_pk_bf16_f32 v69, v86, v87
	v_cvt_pk_bf16_f32 v68, v215, v88
	v_cvt_pk_bf16_f32 v67, v214, v89
	v_cvt_pk_bf16_f32 v66, v212, v213
	v_add_f32_e32 v1, v212, v1
	v_add_f32_e32 v1, v213, v1
	s_waitcnt lgkmcnt(6)
	v_mfma_f32_32x32x16_bf16 v[50:65], v[70:73], v[66:69], v[50:65]
	v_add_f32_e32 v1, v214, v1
	v_add_f32_e32 v1, v89, v1
	v_add_f32_e32 v1, v215, v1
	v_add_f32_e32 v1, v88, v1
	v_add_f32_e32 v1, v86, v1
	v_add_f32_e32 v1, v87, v1
	v_add_f32_e32 v186, v186, v1
	s_waitcnt lgkmcnt(2)
	v_mfma_f32_32x32x16_bf16 v[34:49], v[74:77], v[66:69], v[34:49]
	s_waitcnt lgkmcnt(1)
	v_mfma_f32_32x32x16_bf16 v[18:33], v[78:81], v[66:69], v[18:33]
	s_waitcnt lgkmcnt(0)
	v_mfma_f32_32x32x16_bf16 v[2:17], v[82:85], v[66:69], v[2:17]
	s_cbranch_scc1 .LBB0_1207

.LBB0_1203:
	v_add3_u32 v1, s56, v202, v203
	s_waitcnt lgkmcnt(0)
	s_barrier
	ds_read_b128 v[66:69], v1
	ds_read_b128 v[212:215], v1 offset:32
	s_waitcnt lgkmcnt(1)
	v_mfma_f32_32x32x16_bf16 v[82:97], v[66:69], v[118:121], v[232:247]
	ds_read_b128 v[66:69], v1 offset:12800
	ds_read_b128 v[216:219], v1 offset:12832
	s_cmp_le_i32 s55, s52
	s_waitcnt lgkmcnt(1)
	v_mfma_f32_32x32x16_bf16 v[66:81], v[66:69], v[118:121], v[232:247]
	v_mfma_f32_32x32x16_bf16 v[82:97], v[212:215], v[122:125], v[82:97]
	s_waitcnt lgkmcnt(0)
	v_mfma_f32_32x32x16_bf16 v[66:81], v[216:219], v[122:125], v[66:81]
	ds_read_b128 v[212:215], v1 offset:64
	ds_read_b128 v[216:219], v1 offset:96
	s_waitcnt lgkmcnt(1)
	v_mfma_f32_32x32x16_bf16 v[82:97], v[212:215], v[126:129], v[82:97]
	ds_read_b128 v[212:215], v1 offset:12864
	ds_read_b128 v[220:223], v1 offset:12896
	s_waitcnt lgkmcnt(1)
	v_mfma_f32_32x32x16_bf16 v[66:81], v[212:215], v[126:129], v[66:81]
	v_mfma_f32_32x32x16_bf16 v[82:97], v[216:219], v[130:133], v[82:97]
	ds_read_b128 v[212:215], v1 offset:128
	ds_read_b128 v[216:219], v1 offset:160
	s_waitcnt lgkmcnt(2)
	v_mfma_f32_32x32x16_bf16 v[66:81], v[220:223], v[130:133], v[66:81]
	s_waitcnt lgkmcnt(1)
	v_mfma_f32_32x32x16_bf16 v[82:97], v[212:215], v[134:137], v[82:97]
	ds_read_b128 v[212:215], v1 offset:12928
	ds_read_b128 v[220:223], v1 offset:12960
	s_waitcnt lgkmcnt(1)
	v_mfma_f32_32x32x16_bf16 v[66:81], v[212:215], v[134:137], v[66:81]
	v_mfma_f32_32x32x16_bf16 v[82:97], v[216:219], v[138:141], v[82:97]
	ds_read_b128 v[212:215], v1 offset:192
	ds_read_b128 v[216:219], v1 offset:224
	s_waitcnt lgkmcnt(2)
	v_mfma_f32_32x32x16_bf16 v[66:81], v[220:223], v[138:141], v[66:81]
	s_waitcnt lgkmcnt(1)
	v_mfma_f32_32x32x16_bf16 v[82:97], v[212:215], v[142:145], v[82:97]
	ds_read_b128 v[212:215], v1 offset:12992
	ds_read_b128 v[220:223], v1 offset:13024
	s_waitcnt lgkmcnt(1)
	v_mfma_f32_32x32x16_bf16 v[66:81], v[212:215], v[142:145], v[66:81]
	v_mfma_f32_32x32x16_bf16 v[82:97], v[216:219], v[146:149], v[82:97]
	ds_read_b128 v[212:215], v1 offset:256
	ds_read_b128 v[216:219], v1 offset:288
	s_waitcnt lgkmcnt(2)
	v_mfma_f32_32x32x16_bf16 v[66:81], v[220:223], v[146:149], v[66:81]
	s_waitcnt lgkmcnt(1)
	v_mfma_f32_32x32x16_bf16 v[82:97], v[212:215], v[150:153], v[82:97]
	ds_read_b128 v[212:215], v1 offset:13056
	ds_read_b128 v[220:223], v1 offset:13088
	s_waitcnt lgkmcnt(1)
	v_mfma_f32_32x32x16_bf16 v[66:81], v[212:215], v[150:153], v[66:81]
	v_mfma_f32_32x32x16_bf16 v[82:97], v[216:219], v[154:157], v[82:97]
	ds_read_b128 v[212:215], v1 offset:320
	ds_read_b128 v[216:219], v1 offset:352
	s_waitcnt lgkmcnt(2)
	v_mfma_f32_32x32x16_bf16 v[66:81], v[220:223], v[154:157], v[66:81]
	s_waitcnt lgkmcnt(1)
	v_mfma_f32_32x32x16_bf16 v[82:97], v[212:215], v[158:161], v[82:97]
	ds_read_b128 v[212:215], v1 offset:13120
	ds_read_b128 v[220:223], v1 offset:13152
	s_waitcnt lgkmcnt(1)
	v_mfma_f32_32x32x16_bf16 v[66:81], v[212:215], v[158:161], v[66:81]
	v_mfma_f32_32x32x16_bf16 v[82:97], v[216:219], v[162:165], v[82:97]
	s_waitcnt lgkmcnt(0)
	v_mfma_f32_32x32x16_bf16 v[66:81], v[220:223], v[162:165], v[66:81]
	s_cbranch_scc1 .LBB0_1205
	v_add_u32_e32 v1, s55, v194
	v_subrev_u32_e32 v207, 63, v1
	v_cmp_le_i32_e32 vcc, v207, v193
	s_nop 5
	v_cndmask_b32_e32 v82, v182, v82, vcc
	v_cmp_lt_i32_e32 vcc, v207, v193
	v_subrev_u32_e32 v207, 61, v1
	s_nop 0
	v_cndmask_b32_e32 v83, v182, v83, vcc
	v_cmp_le_i32_e32 vcc, v207, v193
	v_subrev_u32_e32 v207, 60, v1
	s_nop 0
	v_cndmask_b32_e32 v84, v182, v84, vcc
	v_cmp_le_i32_e32 vcc, v207, v193
	v_subrev_u32_e32 v207, 55, v1
	s_nop 0
	v_cndmask_b32_e32 v85, v182, v85, vcc
	v_cmp_le_i32_e32 vcc, v207, v193
	v_subrev_u32_e32 v207, 54, v1
	s_nop 0
	v_cndmask_b32_e32 v86, v182, v86, vcc
	v_cmp_le_i32_e32 vcc, v207, v193
	v_subrev_u32_e32 v207, 53, v1
	s_nop 0
	v_cndmask_b32_e32 v87, v182, v87, vcc
	v_cmp_le_i32_e32 vcc, v207, v193
	v_subrev_u32_e32 v207, 52, v1
	s_nop 0
	v_cndmask_b32_e32 v88, v182, v88, vcc
	v_cmp_le_i32_e32 vcc, v207, v193
	v_subrev_u32_e32 v207, 47, v1
	s_nop 0
	v_cndmask_b32_e32 v89, v182, v89, vcc
	v_cmp_le_i32_e32 vcc, v207, v193
	v_subrev_u32_e32 v207, 46, v1
	s_nop 0
	v_cndmask_b32_e32 v90, v182, v90, vcc
	v_cmp_le_i32_e32 vcc, v207, v193
	v_subrev_u32_e32 v207, 45, v1
	s_nop 0
	v_cndmask_b32_e32 v91, v182, v91, vcc
	v_cmp_le_i32_e32 vcc, v207, v193
	v_subrev_u32_e32 v207, 44, v1
	s_nop 0
	v_cndmask_b32_e32 v92, v182, v92, vcc
	v_cmp_le_i32_e32 vcc, v207, v193
	v_subrev_u32_e32 v207, 39, v1
	s_nop 0
	v_cndmask_b32_e32 v93, v182, v93, vcc
	v_cmp_le_i32_e32 vcc, v207, v193
	v_subrev_u32_e32 v207, 38, v1
	s_nop 0
	v_cndmask_b32_e32 v94, v182, v94, vcc
	v_cmp_le_i32_e32 vcc, v207, v193
	v_subrev_u32_e32 v207, 37, v1
	s_nop 0
	v_cndmask_b32_e32 v95, v182, v95, vcc
	v_cmp_le_i32_e32 vcc, v207, v193
	v_subrev_u32_e32 v207, 36, v1
	s_nop 0
	v_cndmask_b32_e32 v96, v182, v96, vcc
	v_cmp_le_i32_e32 vcc, v207, v193
	v_subrev_u32_e32 v207, 31, v1
	s_nop 0
	v_cndmask_b32_e32 v97, v182, v97, vcc
	v_cmp_le_i32_e32 vcc, v207, v193
	v_subrev_u32_e32 v207, 30, v1
	s_nop 0
	v_cndmask_b32_e32 v66, v182, v66, vcc
	v_cmp_le_i32_e32 vcc, v207, v193
	v_subrev_u32_e32 v207, 29, v1
	s_nop 0
	v_cndmask_b32_e32 v67, v182, v67, vcc
	v_cmp_le_i32_e32 vcc, v207, v193
	v_subrev_u32_e32 v207, 28, v1
	s_nop 0
	v_cndmask_b32_e32 v68, v182, v68, vcc
	v_cmp_le_i32_e32 vcc, v207, v193
	v_subrev_u32_e32 v207, 23, v1
	s_nop 0
	v_cndmask_b32_e32 v69, v182, v69, vcc
	v_cmp_le_i32_e32 vcc, v207, v193
	v_subrev_u32_e32 v207, 22, v1
	s_nop 0
	v_cndmask_b32_e32 v70, v182, v70, vcc
	v_cmp_le_i32_e32 vcc, v207, v193
	v_subrev_u32_e32 v207, 21, v1
	s_nop 0
	v_cndmask_b32_e32 v71, v182, v71, vcc
	v_cmp_le_i32_e32 vcc, v207, v193
	v_subrev_u32_e32 v207, 20, v1
	s_nop 0
	v_cndmask_b32_e32 v72, v182, v72, vcc
	v_cmp_le_i32_e32 vcc, v207, v193
	v_add_u32_e32 v207, -15, v1
	s_nop 0
	v_cndmask_b32_e32 v73, v182, v73, vcc
	v_cmp_le_i32_e32 vcc, v207, v193
	v_add_u32_e32 v207, -14, v1
	s_nop 0
	v_cndmask_b32_e32 v74, v182, v74, vcc
	v_cmp_le_i32_e32 vcc, v207, v193
	v_add_u32_e32 v207, -13, v1
	s_nop 0
	v_cndmask_b32_e32 v75, v182, v75, vcc
	v_cmp_le_i32_e32 vcc, v207, v193
	v_add_u32_e32 v207, -12, v1
	s_nop 0
	v_cndmask_b32_e32 v76, v182, v76, vcc
	v_cmp_le_i32_e32 vcc, v207, v193
	v_add_u32_e32 v207, -7, v1
	s_nop 0
	v_cndmask_b32_e32 v77, v182, v77, vcc
	v_cmp_le_i32_e32 vcc, v207, v193
	v_add_u32_e32 v207, -6, v1
	s_nop 0
	v_cndmask_b32_e32 v78, v182, v78, vcc
	v_cmp_le_i32_e32 vcc, v207, v193
	v_add_u32_e32 v207, -5, v1
	v_add_u32_e32 v1, -4, v1
	v_cndmask_b32_e32 v79, v182, v79, vcc
	v_cmp_le_i32_e32 vcc, v207, v193
	s_nop 1
	v_cndmask_b32_e32 v80, v182, v80, vcc
	v_cmp_le_i32_e32 vcc, v1, v193
	s_nop 1
	v_cndmask_b32_e32 v81, v182, v81, vcc
.LBB0_1205:
	s_nop 8
	v_max3_f32 v1, v82, s48, v83
	v_max3_f32 v1, v1, v84, v85
	v_max3_f32 v1, v1, v86, v87
	v_max3_f32 v1, v1, v88, v89
	v_max3_f32 v1, v1, v90, v91
	v_max3_f32 v1, v1, v92, v93
	v_max3_f32 v1, v1, v94, v95
	v_max3_f32 v1, v1, v96, v97
	v_max3_f32 v1, v1, v66, v67
	v_max3_f32 v1, v1, v68, v69
	v_max3_f32 v1, v1, v70, v71
	v_max3_f32 v1, v1, v72, v73
	v_max3_f32 v1, v1, v74, v75
	v_max3_f32 v1, v1, v76, v77
	v_max3_f32 v1, v1, v78, v79
	v_max3_f32 v1, v1, v80, v81
	ds_bpermute_b32 v207, v180, v1
	s_waitcnt lgkmcnt(0)
	v_max_f32_e32 v207, v207, v207
	v_max_f32_e32 v1, v1, v207
	v_add_f32_e32 v207, 0x41000000, v249
	v_cmp_gt_f32_e32 vcc, v1, v207
	s_cbranch_vccz .LBB0_1200
	v_max_f32_e32 v1, v1, v1
	v_max_f32_e32 v250, v249, v249
	v_max_f32_e32 v250, v250, v1
	v_sub_f32_e32 v251, v250, v248
	v_sub_f32_e32 v206, v249, v250
	v_exp_f32_e32 v206, v206
	s_nop 0
	v_pk_mul_f32 v[64:65], v[64:65], v[206:207] op_sel_hi:[1,0]
	v_pk_mul_f32 v[62:63], v[62:63], v[206:207] op_sel_hi:[1,0]
	v_pk_mul_f32 v[60:61], v[60:61], v[206:207] op_sel_hi:[1,0]
	v_pk_mul_f32 v[58:59], v[58:59], v[206:207] op_sel_hi:[1,0]
	v_pk_mul_f32 v[56:57], v[56:57], v[206:207] op_sel_hi:[1,0]
	v_pk_mul_f32 v[54:55], v[54:55], v[206:207] op_sel_hi:[1,0]
	v_pk_mul_f32 v[52:53], v[52:53], v[206:207] op_sel_hi:[1,0]
	v_pk_mul_f32 v[50:51], v[50:51], v[206:207] op_sel_hi:[1,0]
	v_pk_mul_f32 v[48:49], v[48:49], v[206:207] op_sel_hi:[1,0]
	v_pk_mul_f32 v[46:47], v[46:47], v[206:207] op_sel_hi:[1,0]
	v_pk_mul_f32 v[44:45], v[44:45], v[206:207] op_sel_hi:[1,0]
	v_pk_mul_f32 v[42:43], v[42:43], v[206:207] op_sel_hi:[1,0]
	v_pk_mul_f32 v[40:41], v[40:41], v[206:207] op_sel_hi:[1,0]
	v_pk_mul_f32 v[38:39], v[38:39], v[206:207] op_sel_hi:[1,0]
	v_pk_mul_f32 v[36:37], v[36:37], v[206:207] op_sel_hi:[1,0]
	v_pk_mul_f32 v[34:35], v[34:35], v[206:207] op_sel_hi:[1,0]
	v_pk_mul_f32 v[32:33], v[32:33], v[206:207] op_sel_hi:[1,0]
	v_pk_mul_f32 v[30:31], v[30:31], v[206:207] op_sel_hi:[1,0]
	v_pk_mul_f32 v[28:29], v[28:29], v[206:207] op_sel_hi:[1,0]
	v_pk_mul_f32 v[26:27], v[26:27], v[206:207] op_sel_hi:[1,0]
	v_pk_mul_f32 v[24:25], v[24:25], v[206:207] op_sel_hi:[1,0]
	v_pk_mul_f32 v[22:23], v[22:23], v[206:207] op_sel_hi:[1,0]
	v_pk_mul_f32 v[20:21], v[20:21], v[206:207] op_sel_hi:[1,0]
	v_pk_mul_f32 v[18:19], v[18:19], v[206:207] op_sel_hi:[1,0]
	v_pk_mul_f32 v[16:17], v[16:17], v[206:207] op_sel_hi:[1,0]
	v_pk_mul_f32 v[14:15], v[14:15], v[206:207] op_sel_hi:[1,0]
	v_pk_mul_f32 v[12:13], v[12:13], v[206:207] op_sel_hi:[1,0]
	v_pk_mul_f32 v[10:11], v[10:11], v[206:207] op_sel_hi:[1,0]
	v_pk_mul_f32 v[8:9], v[8:9], v[206:207] op_sel_hi:[1,0]
	v_pk_mul_f32 v[6:7], v[6:7], v[206:207] op_sel_hi:[1,0]
	v_pk_mul_f32 v[4:5], v[4:5], v[206:207] op_sel_hi:[1,0]
	v_pk_mul_f32 v[2:3], v[2:3], v[206:207] op_sel_hi:[1,0]
	v_mul_f32_e32 v186, v186, v206
	v_mov_b32_e32 v206, v251
	v_xor_b32_e32 v250, 0x80000000, v251
	v_cmp_lt_f32_e32 vcc, 0xf0a18f08, v251
	s_nop 1
	v_cndmask_b32_e32 v250, 0, v250, vcc
	v_add_f32_e32 v249, v251, v250
	v_sub_f32_e32 v251, v250, v248
	v_mov_b32_e32 v248, v250
	v_add_f32_e32 v66, v251, v66
	v_add_f32_e32 v67, v251, v67
	v_add_f32_e32 v68, v251, v68
	v_add_f32_e32 v69, v251, v69
	v_add_f32_e32 v70, v251, v70
	v_add_f32_e32 v71, v251, v71
	v_add_f32_e32 v72, v251, v72
	v_add_f32_e32 v73, v251, v73
	v_add_f32_e32 v74, v251, v74
	v_add_f32_e32 v75, v251, v75
	v_add_f32_e32 v76, v251, v76
	v_add_f32_e32 v77, v251, v77
	v_add_f32_e32 v78, v251, v78
	v_add_f32_e32 v79, v251, v79
	v_add_f32_e32 v80, v251, v80
	v_add_f32_e32 v81, v251, v81
	v_add_f32_e32 v82, v251, v82
	v_add_f32_e32 v83, v251, v83
	v_add_f32_e32 v84, v251, v84
	v_add_f32_e32 v85, v251, v85
	v_add_f32_e32 v86, v251, v86
	v_add_f32_e32 v87, v251, v87
	v_add_f32_e32 v88, v251, v88
	v_add_f32_e32 v89, v251, v89
	v_add_f32_e32 v90, v251, v90
	v_add_f32_e32 v91, v251, v91
	v_add_f32_e32 v92, v251, v92
	v_add_f32_e32 v93, v251, v93
	v_add_f32_e32 v94, v251, v94
	v_add_f32_e32 v95, v251, v95
	v_add_f32_e32 v96, v251, v96
	v_add_f32_e32 v97, v251, v97
	v_mov_b32_e32 v232, v250
	v_mov_b32_e32 v233, v250
	v_mov_b32_e32 v234, v250
	v_mov_b32_e32 v235, v250
	v_mov_b32_e32 v236, v250
	v_mov_b32_e32 v237, v250
	v_mov_b32_e32 v238, v250
	v_mov_b32_e32 v239, v250
	v_mov_b32_e32 v240, v250
	v_mov_b32_e32 v241, v250
	v_mov_b32_e32 v242, v250
	v_mov_b32_e32 v243, v250
	v_mov_b32_e32 v244, v250
	v_mov_b32_e32 v245, v250
	v_mov_b32_e32 v246, v250
	v_mov_b32_e32 v247, v250
	s_branch .LBB0_1200

.LBB0_2142:
	s_addk_i32 s3, 0x5f
	s_bfe_u32 s10, s26, 0x60006
	s_lshr_b32 s3, s3, 6
	s_add_i32 s10, s10, 1
	s_min_u32 s35, s3, s10
	s_sub_i32 s10, 0, s2
	s_lshr_b32 s2, s21, 6
	s_add_i32 s2, s2, 1
	s_min_u32 s2, s2, s8
	s_max_u32 s11, s2, s9
	s_cmp_le_u32 s2, s9
	s_cbranch_scc1 .LBB0_2151
	v_bfe_u32 v0, v2, 5, 1
	v_lshlrev_b32_e32 v107, 2, v0
	v_lshrrev_b32_e32 v4, 2, v2
	v_and_b32_e32 v3, 31, v2
	v_and_or_b32 v4, v4, 3, v107
	v_and_b32_e32 v32, 16, v2
	v_lshlrev_b32_e32 v2, 2, v2
	v_or_b32_e32 v106, s21, v3
	v_and_b32_e32 v33, 12, v2
	v_mul_u32_u24_e32 v34, 0x48, v3
	v_mul_u32_u24_e32 v109, 0xc0, v4
	v_mov_b32_e32 v2, v1
	v_mov_b32_e32 v3, v1
	v_mov_b32_e32 v4, v1
	v_mov_b32_e32 v5, v1
	v_mov_b32_e32 v6, v1
	v_mov_b32_e32 v7, v1
	v_mov_b32_e32 v8, v1
	v_mov_b32_e32 v9, v1
	v_mov_b32_e32 v10, v1
	v_mov_b32_e32 v11, v1
	v_mov_b32_e32 v12, v1
	v_mov_b32_e32 v13, v1
	v_mov_b32_e32 v14, v1
	v_mov_b32_e32 v15, v1
	v_mov_b32_e32 v16, v1
	v_mov_b32_e32 v17, v1
	v_mov_b32_e32 v18, v1
	v_mov_b32_e32 v19, v1
	v_mov_b32_e32 v20, v1
	v_mov_b32_e32 v21, v1
	v_mov_b32_e32 v22, v1
	v_mov_b32_e32 v23, v1
	v_mov_b32_e32 v24, v1
	v_mov_b32_e32 v25, v1
	v_mov_b32_e32 v26, v1
	v_mov_b32_e32 v27, v1
	v_mov_b32_e32 v28, v1
	v_mov_b32_e32 v29, v1
	v_mov_b32_e32 v30, v1
	v_mov_b32_e32 v31, v1
	v_lshlrev_b32_e32 v108, 4, v0
	v_mov_b32_e32 v0, v1
	s_waitcnt vmcnt(10)
	v_lshlrev_b32_e32 v143, 1, v32
	s_waitcnt vmcnt(9)
	v_lshlrev_b32_e32 v144, 1, v33
	v_mov_b64_e32 v[32:33], v[30:31]
	s_add_i32 s36, s21, 0xffffffa0
	v_add_u32_e32 v110, 0xffffff80, v106
	v_add_u32_e32 v111, 0xffffff7f, v106
	v_add_u32_e32 v112, 0xffffff7e, v106
	v_add_u32_e32 v113, 0xffffff7d, v106
	v_add_u32_e32 v114, 0xffffff78, v106
	v_add_u32_e32 v115, 0xffffff77, v106
	v_add_u32_e32 v116, 0xffffff76, v106
	v_add_u32_e32 v117, 0xffffff75, v106
	v_add_u32_e32 v118, 0xffffff70, v106
	v_add_u32_e32 v119, 0xffffff6f, v106
	v_add_u32_e32 v120, 0xffffff6e, v106
	v_add_u32_e32 v121, 0xffffff6d, v106
	v_add_u32_e32 v122, 0xffffff68, v106
	v_add_u32_e32 v123, 0xffffff67, v106
	v_add_u32_e32 v124, 0xffffff66, v106
	v_add_u32_e32 v125, 0xffffff65, v106
	v_add_u32_e32 v126, 0xffffff60, v106
	v_add_u32_e32 v127, 0xffffff5f, v106
	v_add_u32_e32 v128, 0xffffff5e, v106
	v_add_u32_e32 v129, 0xffffff5d, v106
	v_add_u32_e32 v130, 0xffffff58, v106
	v_add_u32_e32 v131, 0xffffff57, v106
	v_add_u32_e32 v132, 0xffffff56, v106
	v_add_u32_e32 v133, 0xffffff55, v106
	v_add_u32_e32 v134, 0xffffff50, v106
	v_add_u32_e32 v135, 0xffffff4f, v106
	v_add_u32_e32 v136, 0xffffff4e, v106
	v_add_u32_e32 v137, 0xffffff4d, v106
	v_add_u32_e32 v138, 0xffffff48, v106
	v_add_u32_e32 v139, 0xffffff47, v106
	v_add_u32_e32 v140, 0xffffff46, v106
	v_add_u32_e32 v141, 0xffffff45, v106
	s_lshl_b32 s37, s9, 6
	v_mov_b32_e32 v101, 0
	v_mov_b32_e32 v105, 0xf149f2ca
	v_mov_b32_e32 v212, 0
	v_mov_b32_e32 v213, 0
	v_mov_b32_e32 v214, 0
	v_mov_b32_e32 v215, 0
	v_mov_b32_e32 v216, 0
	v_mov_b32_e32 v217, 0
	v_mov_b32_e32 v218, 0
	v_mov_b32_e32 v219, 0
	v_mov_b32_e32 v220, 0
	v_mov_b32_e32 v221, 0
	v_mov_b32_e32 v222, 0
	v_mov_b32_e32 v223, 0
	v_mov_b32_e32 v224, 0
	v_mov_b32_e32 v225, 0
	v_mov_b32_e32 v226, 0
	v_mov_b32_e32 v227, 0
	v_mov_b32_e32 v228, 0
	v_mov_b32_e32 v229, v105
	v_lshlrev_b32_e32 v142, 1, v34
	v_mov_b64_e32 v[30:31], v[28:29]
	v_mov_b64_e32 v[28:29], v[26:27]
	v_mov_b64_e32 v[26:27], v[24:25]
	v_mov_b64_e32 v[24:25], v[22:23]
	v_mov_b64_e32 v[22:23], v[20:21]
	v_mov_b64_e32 v[20:21], v[18:19]
	v_mov_b64_e32 v[18:19], v[16:17]
	v_mov_b64_e32 v[16:17], v[14:15]
	v_mov_b64_e32 v[14:15], v[12:13]
	v_mov_b64_e32 v[12:13], v[10:11]
	v_mov_b64_e32 v[10:11], v[8:9]
	v_mov_b64_e32 v[8:9], v[6:7]
	v_mov_b64_e32 v[6:7], v[4:5]
	v_mov_b64_e32 v[4:5], v[2:3]
	v_mov_b64_e32 v[2:3], v[0:1]
	s_mov_b32 s38, s9
	s_branch .LBB0_2145
.LBB0_2144:
	v_exp_f32_e32 v0, v50
	v_exp_f32_e32 v51, v51
	v_exp_f32_e32 v52, v52
	v_add_u32_e32 v50, s39, v109
	v_exp_f32_e32 v53, v53
	v_add3_u32 v145, v50, v143, v144
	v_add_f32_e32 v50, 0, v0
	v_exp_f32_e32 v54, v54
	v_add_f32_e32 v50, v51, v50
	v_exp_f32_e32 v55, v55
	v_add_f32_e32 v50, v52, v50
	v_exp_f32_e32 v56, v56
	v_add_f32_e32 v50, v53, v50
	v_exp_f32_e32 v57, v57
	v_add_f32_e32 v50, v54, v50
	v_exp_f32_e32 v58, v58
	v_add_f32_e32 v50, v55, v50
	v_exp_f32_e32 v59, v59
	v_add_f32_e32 v50, v56, v50
	v_exp_f32_e32 v60, v60
	v_add_f32_e32 v50, v57, v50
	v_exp_f32_e32 v61, v61
	v_add_f32_e32 v50, v58, v50
	v_exp_f32_e32 v62, v62
	v_add_f32_e32 v50, v59, v50
	v_exp_f32_e32 v63, v63
	v_add_f32_e32 v50, v60, v50
	v_exp_f32_e32 v64, v64
	v_add_f32_e32 v50, v61, v50
	v_exp_f32_e32 v65, v65
	v_add_f32_e32 v50, v62, v50
	v_exp_f32_e32 v146, v34
	v_add_f32_e32 v34, v63, v50
	v_exp_f32_e32 v147, v35
	v_add_f32_e32 v34, v64, v34
	v_exp_f32_e32 v148, v36
	v_add_f32_e32 v34, v65, v34
	v_exp_f32_e32 v149, v37
	v_add_f32_e32 v34, v146, v34
	v_exp_f32_e32 v150, v38
	v_add_f32_e32 v34, v147, v34
	v_add_f32_e32 v34, v148, v34
	v_add_f32_e32 v34, v149, v34
	v_add_f32_e32 v151, v150, v34
	v_exp_f32_e32 v152, v39
	v_exp_f32_e32 v153, v40
	v_exp_f32_e32 v154, v41
	ds_read_b64_tr_b16 v[34:35], v145 offset:9216
	ds_read_b64_tr_b16 v[36:37], v145 offset:10752
	v_exp_f32_e32 v155, v42
	v_cvt_pk_bf16_f32 v39, v52, v53
	v_cvt_pk_bf16_f32 v38, v0, v51
	ds_read_b64_tr_b16 v[52:53], v145 offset:10816
	ds_read_b64_tr_b16 v[50:51], v145 offset:9280
	v_cvt_pk_bf16_f32 v41, v56, v57
	v_cvt_pk_bf16_f32 v40, v54, v55
	v_mov_b32_e32 v54, v43
	s_waitcnt lgkmcnt(2)
	v_mfma_f32_32x32x16_bf16 v[2:17], v[34:37], v[38:41], v[2:17]
	ds_read_b64_tr_b16 v[34:35], v145 offset:12288
	ds_read_b64_tr_b16 v[36:37], v145 offset:13824
	v_exp_f32_e32 v55, v44
	v_exp_f32_e32 v47, v47
	v_add_f32_e32 v0, v152, v151
	v_add_f32_e32 v0, v153, v0
	v_add_f32_e32 v0, v154, v0
	s_waitcnt lgkmcnt(2)
	v_mfma_f32_32x32x16_bf16 v[18:33], v[50:53], v[38:41], v[18:33]
	ds_read_b64_tr_b16 v[52:53], v145 offset:13888
	ds_read_b64_tr_b16 v[50:51], v145 offset:12352
	v_cvt_pk_bf16_f32 v41, v64, v65
	v_cvt_pk_bf16_f32 v40, v62, v63
	v_cvt_pk_bf16_f32 v39, v60, v61
	v_cvt_pk_bf16_f32 v38, v58, v59
	v_add_f32_e32 v0, v155, v0
	s_add_i32 s37, s37, 64
	s_waitcnt lgkmcnt(2)
	v_mfma_f32_32x32x16_bf16 v[2:17], v[34:37], v[38:41], v[2:17]
	v_exp_f32_e32 v56, v45
	v_exp_f32_e32 v46, v46
	ds_read_b64_tr_b16 v[34:35], v145 offset:15360
	ds_read_b64_tr_b16 v[36:37], v145 offset:16896
	ds_read_b64_tr_b16 v[44:45], v145 offset:16960
	ds_read_b64_tr_b16 v[42:43], v145 offset:15424
	s_cmp_ge_u32 s38, s11
	s_waitcnt lgkmcnt(4)
	v_mfma_f32_32x32x16_bf16 v[18:33], v[50:53], v[38:41], v[18:33]
	v_cvt_pk_bf16_f32 v41, v153, v154
	v_cvt_pk_bf16_f32 v40, v150, v152
	v_cvt_pk_bf16_f32 v39, v148, v149
	v_cvt_pk_bf16_f32 v38, v146, v147
	v_exp_f32_e32 v50, v54
	s_nop 0
	v_add_f32_e32 v0, v50, v0
	s_waitcnt lgkmcnt(2)
	v_mfma_f32_32x32x16_bf16 v[2:17], v[34:37], v[38:41], v[2:17]
	v_exp_f32_e32 v48, v48
	v_exp_f32_e32 v49, v49
	ds_read_b64_tr_b16 v[34:35], v145 offset:18432
	ds_read_b64_tr_b16 v[36:37], v145 offset:19968
	v_add_f32_e32 v0, v55, v0
	v_add_f32_e32 v0, v56, v0
	s_waitcnt lgkmcnt(2)
	v_mfma_f32_32x32x16_bf16 v[18:33], v[42:45], v[38:41], v[18:33]
	ds_read_b64_tr_b16 v[44:45], v145 offset:20032
	ds_read_b64_tr_b16 v[42:43], v145 offset:18496
	v_cvt_pk_bf16_f32 v41, v48, v49
	v_cvt_pk_bf16_f32 v40, v46, v47
	v_cvt_pk_bf16_f32 v39, v55, v56
	v_cvt_pk_bf16_f32 v38, v155, v50
	v_add_f32_e32 v0, v46, v0
	v_add_f32_e32 v0, v47, v0
	s_waitcnt lgkmcnt(2)
	v_mfma_f32_32x32x16_bf16 v[2:17], v[34:37], v[38:41], v[2:17]
	v_add_f32_e32 v0, v48, v0
	v_add_f32_e32 v0, v49, v0
	v_add_f32_e32 v101, v101, v0
	s_waitcnt lgkmcnt(0)
	v_mfma_f32_32x32x16_bf16 v[18:33], v[42:45], v[38:41], v[18:33]
	s_cbranch_scc1 .LBB0_2152

.LBB0_2147:
	v_add3_u32 v0, s39, v108, v142
	s_waitcnt lgkmcnt(0)
	s_barrier
	ds_read_b128 v[34:37], v0
	ds_read_b128 v[146:149], v0 offset:32
	s_waitcnt lgkmcnt(1)
	v_mfma_f32_32x32x16_bf16 v[50:65], v[34:37], v[74:77], v[212:227]
	ds_read_b128 v[34:37], v0 offset:4608
	ds_read_b128 v[150:153], v0 offset:4640
	s_add_i32 s14, s37, 63
	s_cmp_lt_i32 s37, s36
	s_cselect_b64 s[2:3], -1, 0
	s_cmp_gt_u32 s14, s21
	s_cselect_b64 s[48:49], -1, 0
	s_or_b64 s[2:3], s[48:49], s[2:3]
	s_waitcnt lgkmcnt(1)
	v_mfma_f32_32x32x16_bf16 v[34:49], v[34:37], v[74:77], v[212:227]
	s_andn2_b64 vcc, exec, s[2:3]
	v_mfma_f32_32x32x16_bf16 v[50:65], v[146:149], v[78:81], v[50:65]
	s_waitcnt lgkmcnt(0)
	v_mfma_f32_32x32x16_bf16 v[34:49], v[150:153], v[78:81], v[34:49]
	ds_read_b128 v[146:149], v0 offset:64
	ds_read_b128 v[150:153], v0 offset:96
	s_waitcnt lgkmcnt(1)
	v_mfma_f32_32x32x16_bf16 v[50:65], v[146:149], v[82:85], v[50:65]
	ds_read_b128 v[146:149], v0 offset:4672
	ds_read_b128 v[154:157], v0 offset:4704
	s_waitcnt lgkmcnt(1)
	v_mfma_f32_32x32x16_bf16 v[34:49], v[146:149], v[82:85], v[34:49]
	v_mfma_f32_32x32x16_bf16 v[50:65], v[150:153], v[86:89], v[50:65]
	s_waitcnt lgkmcnt(0)
	v_mfma_f32_32x32x16_bf16 v[34:49], v[154:157], v[86:89], v[34:49]
	s_cbranch_vccnz .LBB0_2149
	v_add_u32_e32 v0, s37, v107
	v_cmp_le_u32_e32 vcc, v0, v106
	v_cmp_gt_i32_e64 s[2:3], v0, v110
	s_and_b64 vcc, vcc, s[2:3]
	s_nop 4
	v_cndmask_b32_e32 v50, v100, v50, vcc
	v_cmp_lt_u32_e32 vcc, v0, v106
	v_cmp_gt_i32_e64 s[2:3], v0, v111
	s_and_b64 vcc, vcc, s[2:3]
	v_add_u32_e32 v145, 2, v0
	v_cndmask_b32_e32 v51, v100, v51, vcc
	v_cmp_le_i32_e32 vcc, v145, v106
	v_cmp_gt_i32_e64 s[2:3], v0, v112
	s_and_b64 vcc, vcc, s[2:3]
	v_add_u32_e32 v145, 3, v0
	v_cndmask_b32_e32 v52, v100, v52, vcc
	v_cmp_le_i32_e32 vcc, v145, v106
	v_cmp_gt_i32_e64 s[2:3], v0, v113
	s_and_b64 vcc, vcc, s[2:3]
	v_add_u32_e32 v145, 8, v0
	v_cndmask_b32_e32 v53, v100, v53, vcc
	v_cmp_le_i32_e32 vcc, v145, v106
	v_cmp_gt_i32_e64 s[2:3], v0, v114
	s_and_b64 vcc, vcc, s[2:3]
	v_add_u32_e32 v145, 9, v0
	v_cndmask_b32_e32 v54, v100, v54, vcc
	v_cmp_le_i32_e32 vcc, v145, v106
	v_cmp_gt_i32_e64 s[2:3], v0, v115
	s_and_b64 vcc, vcc, s[2:3]
	v_add_u32_e32 v145, 10, v0
	v_cndmask_b32_e32 v55, v100, v55, vcc
	v_cmp_le_i32_e32 vcc, v145, v106
	v_cmp_gt_i32_e64 s[2:3], v0, v116
	s_and_b64 vcc, vcc, s[2:3]
	v_add_u32_e32 v145, 11, v0
	v_cndmask_b32_e32 v56, v100, v56, vcc
	v_cmp_le_i32_e32 vcc, v145, v106
	v_cmp_gt_i32_e64 s[2:3], v0, v117
	s_and_b64 vcc, vcc, s[2:3]
	v_add_u32_e32 v145, 16, v0
	v_cndmask_b32_e32 v57, v100, v57, vcc
	v_cmp_le_i32_e32 vcc, v145, v106
	v_cmp_gt_i32_e64 s[2:3], v0, v118
	s_and_b64 vcc, vcc, s[2:3]
	v_add_u32_e32 v145, 17, v0
	v_cndmask_b32_e32 v58, v100, v58, vcc
	v_cmp_le_i32_e32 vcc, v145, v106
	v_cmp_gt_i32_e64 s[2:3], v0, v119
	s_and_b64 vcc, vcc, s[2:3]
	v_add_u32_e32 v145, 18, v0
	v_cndmask_b32_e32 v59, v100, v59, vcc
	v_cmp_le_i32_e32 vcc, v145, v106
	v_cmp_gt_i32_e64 s[2:3], v0, v120
	s_and_b64 vcc, vcc, s[2:3]
	v_add_u32_e32 v145, 19, v0
	v_cndmask_b32_e32 v60, v100, v60, vcc
	v_cmp_le_i32_e32 vcc, v145, v106
	v_cmp_gt_i32_e64 s[2:3], v0, v121
	s_and_b64 vcc, vcc, s[2:3]
	v_add_u32_e32 v145, 24, v0
	v_cndmask_b32_e32 v61, v100, v61, vcc
	v_cmp_le_i32_e32 vcc, v145, v106
	v_cmp_gt_i32_e64 s[2:3], v0, v122
	s_and_b64 vcc, vcc, s[2:3]
	v_add_u32_e32 v145, 25, v0
	v_cndmask_b32_e32 v62, v100, v62, vcc
	v_cmp_le_i32_e32 vcc, v145, v106
	v_cmp_gt_i32_e64 s[2:3], v0, v123
	s_and_b64 vcc, vcc, s[2:3]
	v_add_u32_e32 v145, 26, v0
	v_cndmask_b32_e32 v63, v100, v63, vcc
	v_cmp_le_i32_e32 vcc, v145, v106
	v_cmp_gt_i32_e64 s[2:3], v0, v124
	s_and_b64 vcc, vcc, s[2:3]
	v_add_u32_e32 v145, 27, v0
	v_cndmask_b32_e32 v64, v100, v64, vcc
	v_cmp_le_i32_e32 vcc, v145, v106
	v_cmp_gt_i32_e64 s[2:3], v0, v125
	s_and_b64 vcc, vcc, s[2:3]
	v_add_u32_e32 v145, 32, v0
	v_cndmask_b32_e32 v65, v100, v65, vcc
	v_cmp_le_i32_e32 vcc, v145, v106
	v_cmp_gt_i32_e64 s[2:3], v0, v126
	s_and_b64 vcc, vcc, s[2:3]
	v_add_u32_e32 v145, 33, v0
	v_cndmask_b32_e32 v34, v100, v34, vcc
	v_cmp_le_i32_e32 vcc, v145, v106
	v_cmp_gt_i32_e64 s[2:3], v0, v127
	s_and_b64 vcc, vcc, s[2:3]
	v_add_u32_e32 v145, 34, v0
	v_cndmask_b32_e32 v35, v100, v35, vcc
	v_cmp_le_i32_e32 vcc, v145, v106
	v_cmp_gt_i32_e64 s[2:3], v0, v128
	s_and_b64 vcc, vcc, s[2:3]
	v_add_u32_e32 v145, 35, v0
	v_cndmask_b32_e32 v36, v100, v36, vcc
	v_cmp_le_i32_e32 vcc, v145, v106
	v_cmp_gt_i32_e64 s[2:3], v0, v129
	s_and_b64 vcc, vcc, s[2:3]
	v_add_u32_e32 v145, 40, v0
	v_cndmask_b32_e32 v37, v100, v37, vcc
	v_cmp_le_i32_e32 vcc, v145, v106
	v_cmp_gt_i32_e64 s[2:3], v0, v130
	s_and_b64 vcc, vcc, s[2:3]
	v_add_u32_e32 v145, 41, v0
	v_cndmask_b32_e32 v38, v100, v38, vcc
	v_cmp_le_i32_e32 vcc, v145, v106
	v_cmp_gt_i32_e64 s[2:3], v0, v131
	s_and_b64 vcc, vcc, s[2:3]
	v_add_u32_e32 v145, 42, v0
	v_cndmask_b32_e32 v39, v100, v39, vcc
	v_cmp_le_i32_e32 vcc, v145, v106
	v_cmp_gt_i32_e64 s[2:3], v0, v132
	s_and_b64 vcc, vcc, s[2:3]
	v_add_u32_e32 v145, 43, v0
	v_cndmask_b32_e32 v40, v100, v40, vcc
	v_cmp_le_i32_e32 vcc, v145, v106
	v_cmp_gt_i32_e64 s[2:3], v0, v133
	s_and_b64 vcc, vcc, s[2:3]
	v_add_u32_e32 v145, 48, v0
	v_cndmask_b32_e32 v41, v100, v41, vcc
	v_cmp_le_i32_e32 vcc, v145, v106
	v_cmp_gt_i32_e64 s[2:3], v0, v134
	s_and_b64 vcc, vcc, s[2:3]
	v_add_u32_e32 v145, 49, v0
	v_cndmask_b32_e32 v42, v100, v42, vcc
	v_cmp_le_i32_e32 vcc, v145, v106
	v_cmp_gt_i32_e64 s[2:3], v0, v135
	s_and_b64 vcc, vcc, s[2:3]
	v_add_u32_e32 v145, 50, v0
	v_cndmask_b32_e32 v43, v100, v43, vcc
	v_cmp_le_i32_e32 vcc, v145, v106
	v_cmp_gt_i32_e64 s[2:3], v0, v136
	s_and_b64 vcc, vcc, s[2:3]
	v_add_u32_e32 v145, 51, v0
	v_cndmask_b32_e32 v44, v100, v44, vcc
	v_cmp_le_i32_e32 vcc, v145, v106
	v_cmp_gt_i32_e64 s[2:3], v0, v137
	s_and_b64 vcc, vcc, s[2:3]
	v_add_u32_e32 v145, 56, v0
	v_cndmask_b32_e32 v45, v100, v45, vcc
	v_cmp_le_i32_e32 vcc, v145, v106
	v_cmp_gt_i32_e64 s[2:3], v0, v138
	s_and_b64 vcc, vcc, s[2:3]
	v_add_u32_e32 v145, 57, v0
	v_cndmask_b32_e32 v46, v100, v46, vcc
	v_cmp_le_i32_e32 vcc, v145, v106
	v_cmp_gt_i32_e64 s[2:3], v0, v139
	s_and_b64 vcc, vcc, s[2:3]
	v_add_u32_e32 v145, 58, v0
	v_cndmask_b32_e32 v47, v100, v47, vcc
	v_cmp_le_i32_e32 vcc, v145, v106
	v_cmp_gt_i32_e64 s[2:3], v0, v140
	s_and_b64 vcc, vcc, s[2:3]
	v_add_u32_e32 v145, 59, v0
	v_cndmask_b32_e32 v48, v100, v48, vcc
	v_cmp_le_i32_e32 vcc, v145, v106
	v_cmp_gt_i32_e64 s[2:3], v0, v141
	s_and_b64 vcc, vcc, s[2:3]
	v_cndmask_b32_e32 v49, v100, v49, vcc
.LBB0_2149:
	s_nop 8
	v_max3_f32 v0, v50, s30, v51
	v_max3_f32 v0, v0, v52, v53
	v_max3_f32 v0, v0, v54, v55
	v_max3_f32 v0, v0, v56, v57
	v_max3_f32 v0, v0, v58, v59
	v_max3_f32 v0, v0, v60, v61
	v_max3_f32 v0, v0, v62, v63
	v_max3_f32 v0, v0, v64, v65
	v_max3_f32 v0, v0, v34, v35
	v_max3_f32 v0, v0, v36, v37
	v_max3_f32 v0, v0, v38, v39
	v_max3_f32 v0, v0, v40, v41
	v_max3_f32 v0, v0, v42, v43
	v_max3_f32 v0, v0, v44, v45
	v_max3_f32 v0, v0, v46, v47
	v_max3_f32 v0, v0, v48, v49
	ds_bpermute_b32 v145, v98, v0
	s_waitcnt lgkmcnt(0)
	v_max_f32_e32 v145, v145, v145
	v_max_f32_e32 v0, v0, v145
	v_add_f32_e32 v145, 0x41000000, v229
	v_cmp_gt_f32_e32 vcc, v0, v145
	s_cbranch_vccz .LBB0_2144
	v_max_f32_e32 v0, v0, v0
	v_max_f32_e32 v230, v229, v229
	v_max_f32_e32 v230, v230, v0
	v_sub_f32_e32 v231, v230, v228
	v_sub_f32_e32 v0, v229, v230
	v_exp_f32_e32 v0, v0
	s_nop 0
	v_pk_mul_f32 v[32:33], v[32:33], v[0:1] op_sel_hi:[1,0]
	v_pk_mul_f32 v[30:31], v[30:31], v[0:1] op_sel_hi:[1,0]
	v_pk_mul_f32 v[28:29], v[28:29], v[0:1] op_sel_hi:[1,0]
	v_pk_mul_f32 v[26:27], v[26:27], v[0:1] op_sel_hi:[1,0]
	v_pk_mul_f32 v[24:25], v[24:25], v[0:1] op_sel_hi:[1,0]
	v_pk_mul_f32 v[22:23], v[22:23], v[0:1] op_sel_hi:[1,0]
	v_pk_mul_f32 v[20:21], v[20:21], v[0:1] op_sel_hi:[1,0]
	v_pk_mul_f32 v[18:19], v[18:19], v[0:1] op_sel_hi:[1,0]
	v_pk_mul_f32 v[16:17], v[16:17], v[0:1] op_sel_hi:[1,0]
	v_pk_mul_f32 v[14:15], v[14:15], v[0:1] op_sel_hi:[1,0]
	v_pk_mul_f32 v[12:13], v[12:13], v[0:1] op_sel_hi:[1,0]
	v_pk_mul_f32 v[10:11], v[10:11], v[0:1] op_sel_hi:[1,0]
	v_pk_mul_f32 v[8:9], v[8:9], v[0:1] op_sel_hi:[1,0]
	v_pk_mul_f32 v[6:7], v[6:7], v[0:1] op_sel_hi:[1,0]
	v_pk_mul_f32 v[4:5], v[4:5], v[0:1] op_sel_hi:[1,0]
	v_pk_mul_f32 v[2:3], v[2:3], v[0:1] op_sel_hi:[1,0]
	v_mul_f32_e32 v101, v101, v0
	v_mov_b32_e32 v105, v231
	v_xor_b32_e32 v230, 0x80000000, v231
	v_cmp_lt_f32_e32 vcc, 0xf0a18f08, v231
	s_nop 1
	v_cndmask_b32_e32 v230, 0, v230, vcc
	v_add_f32_e32 v229, v231, v230
	v_sub_f32_e32 v231, v230, v228
	v_mov_b32_e32 v228, v230
	v_add_f32_e32 v34, v231, v34
	v_add_f32_e32 v35, v231, v35
	v_add_f32_e32 v36, v231, v36
	v_add_f32_e32 v37, v231, v37
	v_add_f32_e32 v38, v231, v38
	v_add_f32_e32 v39, v231, v39
	v_add_f32_e32 v40, v231, v40
	v_add_f32_e32 v41, v231, v41
	v_add_f32_e32 v42, v231, v42
	v_add_f32_e32 v43, v231, v43
	v_add_f32_e32 v44, v231, v44
	v_add_f32_e32 v45, v231, v45
	v_add_f32_e32 v46, v231, v46
	v_add_f32_e32 v47, v231, v47
	v_add_f32_e32 v48, v231, v48
	v_add_f32_e32 v49, v231, v49
	v_add_f32_e32 v50, v231, v50
	v_add_f32_e32 v51, v231, v51
	v_add_f32_e32 v52, v231, v52
	v_add_f32_e32 v53, v231, v53
	v_add_f32_e32 v54, v231, v54
	v_add_f32_e32 v55, v231, v55
	v_add_f32_e32 v56, v231, v56
	v_add_f32_e32 v57, v231, v57
	v_add_f32_e32 v58, v231, v58
	v_add_f32_e32 v59, v231, v59
	v_add_f32_e32 v60, v231, v60
	v_add_f32_e32 v61, v231, v61
	v_add_f32_e32 v62, v231, v62
	v_add_f32_e32 v63, v231, v63
	v_add_f32_e32 v64, v231, v64
	v_add_f32_e32 v65, v231, v65
	v_mov_b32_e32 v212, v230
	v_mov_b32_e32 v213, v230
	v_mov_b32_e32 v214, v230
	v_mov_b32_e32 v215, v230
	v_mov_b32_e32 v216, v230
	v_mov_b32_e32 v217, v230
	v_mov_b32_e32 v218, v230
	v_mov_b32_e32 v219, v230
	v_mov_b32_e32 v220, v230
	v_mov_b32_e32 v221, v230
	v_mov_b32_e32 v222, v230
	v_mov_b32_e32 v223, v230
	v_mov_b32_e32 v224, v230
	v_mov_b32_e32 v225, v230
	v_mov_b32_e32 v226, v230
	v_mov_b32_e32 v227, v230
	s_branch .LBB0_2144

.LBB0_4401:
	s_lshr_b32 s2, s49, 26
	s_add_i32 s2, s2, s48
	s_add_i32 s2, s2, 31
	s_ashr_i32 s2, s2, 6
	s_add_i32 s2, s2, 1
	s_min_i32 s2, s2, s8
	s_max_i32 s5, s2, s6
	s_cmp_le_i32 s2, s6
	v_mov_b32_e32 v127, 0
	s_cbranch_scc1 .LBB0_4410
	v_bfe_u32 v2, v0, 5, 1
	v_and_b32_e32 v3, 31, v0
	v_lshlrev_b32_e32 v194, 2, v2
	v_lshrrev_b32_e32 v4, 2, v0
	v_and_b32_e32 v96, 16, v0
	v_lshlrev_b32_e32 v0, 2, v0
	v_and_or_b32 v4, v4, 3, v194
	v_and_b32_e32 v97, 12, v0
	v_mul_u32_u24_e32 v98, 0x48, v3
	v_mov_b32_e32 v30, v1
	v_mov_b32_e32 v31, v1
	v_or_b32_e32 v193, s48, v3
	v_lshlrev_b32_e32 v195, 4, v2
	v_mul_u32_u24_e32 v196, 0xc0, v4
	v_mov_b32_e32 v0, v1
	v_mov_b32_e32 v2, v1
	v_mov_b32_e32 v3, v1
	v_mov_b32_e32 v4, v1
	v_mov_b32_e32 v5, v1
	v_mov_b32_e32 v6, v1
	v_mov_b32_e32 v7, v1
	v_mov_b32_e32 v8, v1
	v_mov_b32_e32 v9, v1
	v_mov_b32_e32 v10, v1
	v_mov_b32_e32 v11, v1
	v_mov_b32_e32 v12, v1
	v_mov_b32_e32 v13, v1
	v_mov_b32_e32 v14, v1
	v_mov_b32_e32 v15, v1
	v_mov_b32_e32 v16, v1
	v_mov_b32_e32 v17, v1
	v_mov_b32_e32 v18, v1
	v_mov_b32_e32 v19, v1
	v_mov_b32_e32 v20, v1
	v_mov_b32_e32 v21, v1
	v_mov_b32_e32 v22, v1
	v_mov_b32_e32 v23, v1
	v_mov_b32_e32 v24, v1
	v_mov_b32_e32 v25, v1
	v_mov_b32_e32 v26, v1
	v_mov_b32_e32 v27, v1
	v_mov_b32_e32 v28, v1
	v_mov_b32_e32 v29, v1
	v_lshlrev_b32_e32 v197, 1, v98
	v_lshlrev_b32_e32 v198, 1, v96
	v_lshlrev_b32_e32 v199, 1, v97
	s_waitcnt vmcnt(2)
	v_mov_b64_e32 v[126:127], v[30:31]
	s_add_i32 s7, s48, 0xfffffe20
	s_lshl_b32 s9, s6, 6
	s_sub_i32 s10, 0, s4
	v_mov_b32_e32 v192, 0
	v_mov_b32_e32 v200, 0xf149f2ca
	v_mov_b32_e32 v212, 0
	v_mov_b32_e32 v213, 0
	v_mov_b32_e32 v214, 0
	v_mov_b32_e32 v215, 0
	v_mov_b32_e32 v216, 0
	v_mov_b32_e32 v217, 0
	v_mov_b32_e32 v218, 0
	v_mov_b32_e32 v219, 0
	v_mov_b32_e32 v220, 0
	v_mov_b32_e32 v221, 0
	v_mov_b32_e32 v222, 0
	v_mov_b32_e32 v223, 0
	v_mov_b32_e32 v224, 0
	v_mov_b32_e32 v225, 0
	v_mov_b32_e32 v226, 0
	v_mov_b32_e32 v227, 0
	v_mov_b32_e32 v228, 0
	v_mov_b32_e32 v229, v200
	v_mov_b64_e32 v[124:125], v[28:29]
	v_mov_b64_e32 v[122:123], v[26:27]
	v_mov_b64_e32 v[120:121], v[24:25]
	v_mov_b64_e32 v[118:119], v[22:23]
	v_mov_b64_e32 v[116:117], v[20:21]
	v_mov_b64_e32 v[114:115], v[18:19]
	v_mov_b64_e32 v[112:113], v[16:17]
	v_mov_b64_e32 v[110:111], v[14:15]
	v_mov_b64_e32 v[108:109], v[12:13]
	v_mov_b64_e32 v[106:107], v[10:11]
	v_mov_b64_e32 v[104:105], v[8:9]
	v_mov_b64_e32 v[102:103], v[6:7]
	v_mov_b64_e32 v[100:101], v[4:5]
	v_mov_b64_e32 v[98:99], v[2:3]
	v_mov_b64_e32 v[96:97], v[0:1]
	s_branch .LBB0_4404
.LBB0_4403:
	v_exp_f32_e32 v0, v128
	v_exp_f32_e32 v19, v129
	v_exp_f32_e32 v20, v130
	v_add_u32_e32 v18, s11, v196
	v_exp_f32_e32 v21, v131
	v_add3_u32 v22, v18, v198, v199
	v_add_f32_e32 v18, 0, v0
	v_exp_f32_e32 v23, v132
	v_add_f32_e32 v18, v19, v18
	v_exp_f32_e32 v24, v133
	v_add_f32_e32 v18, v20, v18
	v_exp_f32_e32 v25, v134
	v_add_f32_e32 v18, v21, v18
	v_exp_f32_e32 v26, v135
	v_add_f32_e32 v18, v23, v18
	v_exp_f32_e32 v27, v136
	v_add_f32_e32 v18, v24, v18
	v_exp_f32_e32 v28, v137
	v_add_f32_e32 v18, v25, v18
	v_exp_f32_e32 v29, v138
	v_add_f32_e32 v18, v26, v18
	v_exp_f32_e32 v30, v139
	v_add_f32_e32 v18, v27, v18
	v_exp_f32_e32 v31, v140
	v_add_f32_e32 v18, v28, v18
	v_exp_f32_e32 v128, v141
	v_add_f32_e32 v18, v29, v18
	v_exp_f32_e32 v129, v142
	v_add_f32_e32 v18, v30, v18
	v_exp_f32_e32 v130, v143
	v_add_f32_e32 v18, v31, v18
	v_exp_f32_e32 v131, v2
	v_add_f32_e32 v2, v128, v18
	v_exp_f32_e32 v132, v3
	v_add_f32_e32 v2, v129, v2
	v_exp_f32_e32 v133, v4
	v_add_f32_e32 v2, v130, v2
	v_exp_f32_e32 v134, v5
	v_add_f32_e32 v2, v131, v2
	v_exp_f32_e32 v135, v6
	v_add_f32_e32 v2, v132, v2
	v_add_f32_e32 v2, v133, v2
	v_add_f32_e32 v2, v134, v2
	v_add_f32_e32 v136, v135, v2
	v_exp_f32_e32 v137, v7
	v_exp_f32_e32 v138, v8
	v_exp_f32_e32 v139, v9
	ds_read_b64_tr_b16 v[2:3], v22 offset:9216
	ds_read_b64_tr_b16 v[4:5], v22 offset:10752
	v_exp_f32_e32 v140, v10
	v_cvt_pk_bf16_f32 v7, v20, v21
	v_cvt_pk_bf16_f32 v6, v0, v19
	ds_read_b64_tr_b16 v[20:21], v22 offset:10816
	ds_read_b64_tr_b16 v[18:19], v22 offset:9280
	v_cvt_pk_bf16_f32 v9, v25, v26
	v_cvt_pk_bf16_f32 v8, v23, v24
	v_mov_b32_e32 v23, v11
	s_waitcnt lgkmcnt(2)
	v_mfma_f32_32x32x16_bf16 v[96:111], v[2:5], v[6:9], v[96:111]
	ds_read_b64_tr_b16 v[2:3], v22 offset:12288
	ds_read_b64_tr_b16 v[4:5], v22 offset:13824
	v_exp_f32_e32 v24, v12
	v_exp_f32_e32 v15, v15
	v_add_f32_e32 v0, v137, v136
	v_add_f32_e32 v0, v138, v0
	v_add_f32_e32 v0, v139, v0
	s_waitcnt lgkmcnt(2)
	v_mfma_f32_32x32x16_bf16 v[112:127], v[18:21], v[6:9], v[112:127]
	ds_read_b64_tr_b16 v[20:21], v22 offset:13888
	ds_read_b64_tr_b16 v[18:19], v22 offset:12352
	v_cvt_pk_bf16_f32 v9, v129, v130
	v_cvt_pk_bf16_f32 v8, v31, v128
	v_cvt_pk_bf16_f32 v7, v29, v30
	v_cvt_pk_bf16_f32 v6, v27, v28
	v_add_f32_e32 v0, v140, v0
	s_add_i32 s9, s9, 64
	s_waitcnt lgkmcnt(2)
	v_mfma_f32_32x32x16_bf16 v[96:111], v[2:5], v[6:9], v[96:111]
	v_exp_f32_e32 v25, v13
	v_exp_f32_e32 v14, v14
	ds_read_b64_tr_b16 v[2:3], v22 offset:15360
	ds_read_b64_tr_b16 v[4:5], v22 offset:16896
	ds_read_b64_tr_b16 v[12:13], v22 offset:16960
	ds_read_b64_tr_b16 v[10:11], v22 offset:15424
	s_cmp_ge_u32 s6, s5
	s_waitcnt lgkmcnt(4)
	v_mfma_f32_32x32x16_bf16 v[112:127], v[18:21], v[6:9], v[112:127]
	v_cvt_pk_bf16_f32 v9, v138, v139
	v_cvt_pk_bf16_f32 v8, v135, v137
	v_cvt_pk_bf16_f32 v7, v133, v134
	v_cvt_pk_bf16_f32 v6, v131, v132
	v_exp_f32_e32 v18, v23
	s_nop 0
	v_add_f32_e32 v0, v18, v0
	s_waitcnt lgkmcnt(2)
	v_mfma_f32_32x32x16_bf16 v[96:111], v[2:5], v[6:9], v[96:111]
	v_exp_f32_e32 v16, v16
	v_exp_f32_e32 v17, v17
	ds_read_b64_tr_b16 v[2:3], v22 offset:18432
	ds_read_b64_tr_b16 v[4:5], v22 offset:19968
	v_add_f32_e32 v0, v24, v0
	v_add_f32_e32 v0, v25, v0
	s_waitcnt lgkmcnt(2)
	v_mfma_f32_32x32x16_bf16 v[112:127], v[10:13], v[6:9], v[112:127]
	ds_read_b64_tr_b16 v[12:13], v22 offset:20032
	ds_read_b64_tr_b16 v[10:11], v22 offset:18496
	v_cvt_pk_bf16_f32 v9, v16, v17
	v_cvt_pk_bf16_f32 v8, v14, v15
	v_cvt_pk_bf16_f32 v7, v24, v25
	v_cvt_pk_bf16_f32 v6, v140, v18
	v_add_f32_e32 v0, v14, v0
	v_add_f32_e32 v0, v15, v0
	s_waitcnt lgkmcnt(2)
	v_mfma_f32_32x32x16_bf16 v[96:111], v[2:5], v[6:9], v[96:111]
	v_add_f32_e32 v0, v16, v0
	v_add_f32_e32 v0, v17, v0
	v_add_f32_e32 v192, v192, v0
	s_waitcnt lgkmcnt(0)
	v_mfma_f32_32x32x16_bf16 v[112:127], v[10:13], v[6:9], v[112:127]
	s_cbranch_scc1 .LBB0_4411

.LBB0_4406:
	v_add3_u32 v0, s11, v195, v197
	s_waitcnt lgkmcnt(0)
	s_barrier
	ds_read_b128 v[2:5], v0
	ds_read_b128 v[18:21], v0 offset:32
	s_waitcnt lgkmcnt(1)
	v_mfma_f32_32x32x16_bf16 v[128:143], v[2:5], v[144:147], v[212:227]
	ds_read_b128 v[2:5], v0 offset:4608
	ds_read_b128 v[22:25], v0 offset:4640
	s_add_i32 s12, s9, 63
	s_cmp_ge_i32 s9, s7
	s_cselect_b64 s[2:3], -1, 0
	s_cmp_le_i32 s12, s48
	s_cselect_b64 s[12:13], -1, 0
	s_and_b64 s[2:3], s[2:3], s[12:13]
	s_waitcnt lgkmcnt(1)
	v_mfma_f32_32x32x16_bf16 v[2:17], v[2:5], v[144:147], v[212:227]
	s_and_b64 vcc, exec, s[2:3]
	v_mfma_f32_32x32x16_bf16 v[128:143], v[18:21], v[148:151], v[128:143]
	s_waitcnt lgkmcnt(0)
	v_mfma_f32_32x32x16_bf16 v[2:17], v[22:25], v[148:151], v[2:17]
	ds_read_b128 v[18:21], v0 offset:64
	ds_read_b128 v[22:25], v0 offset:96
	s_waitcnt lgkmcnt(1)
	v_mfma_f32_32x32x16_bf16 v[128:143], v[18:21], v[152:155], v[128:143]
	ds_read_b128 v[18:21], v0 offset:4672
	ds_read_b128 v[26:29], v0 offset:4704
	s_waitcnt lgkmcnt(1)
	v_mfma_f32_32x32x16_bf16 v[2:17], v[18:21], v[152:155], v[2:17]
	v_mfma_f32_32x32x16_bf16 v[128:143], v[22:25], v[156:159], v[128:143]
	s_waitcnt lgkmcnt(0)
	v_mfma_f32_32x32x16_bf16 v[2:17], v[26:29], v[156:159], v[2:17]
	s_cbranch_vccnz .LBB0_4408
	v_add_u32_e32 v0, s9, v194
	v_add_u32_e32 v18, 0x200, v0
	v_cmp_le_i32_e32 vcc, v0, v193
	v_cmp_gt_i32_e64 s[2:3], v18, v193
	s_and_b64 vcc, vcc, s[2:3]
	v_add_u32_e32 v18, 0x201, v0
	s_nop 2
	v_cndmask_b32_e32 v128, v185, v128, vcc
	v_cmp_lt_i32_e32 vcc, v0, v193
	v_cmp_gt_i32_e64 s[2:3], v18, v193
	s_and_b64 vcc, vcc, s[2:3]
	v_add_u32_e32 v18, 2, v0
	v_cndmask_b32_e32 v129, v185, v129, vcc
	v_cmp_le_i32_e32 vcc, v18, v193
	v_add_u32_e32 v18, 0x202, v0
	v_cmp_gt_i32_e64 s[2:3], v18, v193
	s_and_b64 vcc, vcc, s[2:3]
	v_add_u32_e32 v18, 3, v0
	v_cndmask_b32_e32 v130, v185, v130, vcc
	v_cmp_le_i32_e32 vcc, v18, v193
	v_add_u32_e32 v18, 0x203, v0
	v_cmp_gt_i32_e64 s[2:3], v18, v193
	s_and_b64 vcc, vcc, s[2:3]
	v_add_u32_e32 v18, 8, v0
	v_cndmask_b32_e32 v131, v185, v131, vcc
	v_cmp_le_i32_e32 vcc, v18, v193
	v_add_u32_e32 v18, 0x208, v0
	v_cmp_gt_i32_e64 s[2:3], v18, v193
	s_and_b64 vcc, vcc, s[2:3]
	v_add_u32_e32 v18, 9, v0
	v_cndmask_b32_e32 v132, v185, v132, vcc
	v_cmp_le_i32_e32 vcc, v18, v193
	v_add_u32_e32 v18, 0x209, v0
	v_cmp_gt_i32_e64 s[2:3], v18, v193
	s_and_b64 vcc, vcc, s[2:3]
	v_add_u32_e32 v18, 10, v0
	v_cndmask_b32_e32 v133, v185, v133, vcc
	v_cmp_le_i32_e32 vcc, v18, v193
	v_add_u32_e32 v18, 0x20a, v0
	v_cmp_gt_i32_e64 s[2:3], v18, v193
	s_and_b64 vcc, vcc, s[2:3]
	v_add_u32_e32 v18, 11, v0
	v_cndmask_b32_e32 v134, v185, v134, vcc
	v_cmp_le_i32_e32 vcc, v18, v193
	v_add_u32_e32 v18, 0x20b, v0
	v_cmp_gt_i32_e64 s[2:3], v18, v193
	s_and_b64 vcc, vcc, s[2:3]
	v_add_u32_e32 v18, 16, v0
	v_cndmask_b32_e32 v135, v185, v135, vcc
	v_cmp_le_i32_e32 vcc, v18, v193
	v_add_u32_e32 v18, 0x210, v0
	v_cmp_gt_i32_e64 s[2:3], v18, v193
	s_and_b64 vcc, vcc, s[2:3]
	v_add_u32_e32 v18, 17, v0
	v_cndmask_b32_e32 v136, v185, v136, vcc
	v_cmp_le_i32_e32 vcc, v18, v193
	v_add_u32_e32 v18, 0x211, v0
	v_cmp_gt_i32_e64 s[2:3], v18, v193
	s_and_b64 vcc, vcc, s[2:3]
	v_add_u32_e32 v18, 18, v0
	v_cndmask_b32_e32 v137, v185, v137, vcc
	v_cmp_le_i32_e32 vcc, v18, v193
	v_add_u32_e32 v18, 0x212, v0
	v_cmp_gt_i32_e64 s[2:3], v18, v193
	s_and_b64 vcc, vcc, s[2:3]
	v_add_u32_e32 v18, 19, v0
	v_cndmask_b32_e32 v138, v185, v138, vcc
	v_cmp_le_i32_e32 vcc, v18, v193
	v_add_u32_e32 v18, 0x213, v0
	v_cmp_gt_i32_e64 s[2:3], v18, v193
	s_and_b64 vcc, vcc, s[2:3]
	v_add_u32_e32 v18, 24, v0
	v_cndmask_b32_e32 v139, v185, v139, vcc
	v_cmp_le_i32_e32 vcc, v18, v193
	v_add_u32_e32 v18, 0x218, v0
	v_cmp_gt_i32_e64 s[2:3], v18, v193
	s_and_b64 vcc, vcc, s[2:3]
	v_add_u32_e32 v18, 25, v0
	v_cndmask_b32_e32 v140, v185, v140, vcc
	v_cmp_le_i32_e32 vcc, v18, v193
	v_add_u32_e32 v18, 0x219, v0
	v_cmp_gt_i32_e64 s[2:3], v18, v193
	s_and_b64 vcc, vcc, s[2:3]
	v_add_u32_e32 v18, 26, v0
	v_cndmask_b32_e32 v141, v185, v141, vcc
	v_cmp_le_i32_e32 vcc, v18, v193
	v_add_u32_e32 v18, 0x21a, v0
	v_cmp_gt_i32_e64 s[2:3], v18, v193
	s_and_b64 vcc, vcc, s[2:3]
	v_add_u32_e32 v18, 27, v0
	v_cndmask_b32_e32 v142, v185, v142, vcc
	v_cmp_le_i32_e32 vcc, v18, v193
	v_add_u32_e32 v18, 0x21b, v0
	v_cmp_gt_i32_e64 s[2:3], v18, v193
	s_and_b64 vcc, vcc, s[2:3]
	v_add_u32_e32 v18, 32, v0
	v_cndmask_b32_e32 v143, v185, v143, vcc
	v_cmp_le_i32_e32 vcc, v18, v193
	v_add_u32_e32 v18, 0x220, v0
	v_cmp_gt_i32_e64 s[2:3], v18, v193
	s_and_b64 vcc, vcc, s[2:3]
	v_add_u32_e32 v18, 33, v0
	v_cndmask_b32_e32 v2, v185, v2, vcc
	v_cmp_le_i32_e32 vcc, v18, v193
	v_add_u32_e32 v18, 0x221, v0
	v_cmp_gt_i32_e64 s[2:3], v18, v193
	s_and_b64 vcc, vcc, s[2:3]
	v_add_u32_e32 v18, 34, v0
	v_cndmask_b32_e32 v3, v185, v3, vcc
	v_cmp_le_i32_e32 vcc, v18, v193
	v_add_u32_e32 v18, 0x222, v0
	v_cmp_gt_i32_e64 s[2:3], v18, v193
	s_and_b64 vcc, vcc, s[2:3]
	v_add_u32_e32 v18, 35, v0
	v_cndmask_b32_e32 v4, v185, v4, vcc
	v_cmp_le_i32_e32 vcc, v18, v193
	v_add_u32_e32 v18, 0x223, v0
	v_cmp_gt_i32_e64 s[2:3], v18, v193
	s_and_b64 vcc, vcc, s[2:3]
	v_add_u32_e32 v18, 40, v0
	v_cndmask_b32_e32 v5, v185, v5, vcc
	v_cmp_le_i32_e32 vcc, v18, v193
	v_add_u32_e32 v18, 0x228, v0
	v_cmp_gt_i32_e64 s[2:3], v18, v193
	s_and_b64 vcc, vcc, s[2:3]
	v_add_u32_e32 v18, 41, v0
	v_cndmask_b32_e32 v6, v185, v6, vcc
	v_cmp_le_i32_e32 vcc, v18, v193
	v_add_u32_e32 v18, 0x229, v0
	v_cmp_gt_i32_e64 s[2:3], v18, v193
	s_and_b64 vcc, vcc, s[2:3]
	v_add_u32_e32 v18, 42, v0
	v_cndmask_b32_e32 v7, v185, v7, vcc
	v_cmp_le_i32_e32 vcc, v18, v193
	v_add_u32_e32 v18, 0x22a, v0
	v_cmp_gt_i32_e64 s[2:3], v18, v193
	s_and_b64 vcc, vcc, s[2:3]
	v_add_u32_e32 v18, 43, v0
	v_cndmask_b32_e32 v8, v185, v8, vcc
	v_cmp_le_i32_e32 vcc, v18, v193
	v_add_u32_e32 v18, 0x22b, v0
	v_cmp_gt_i32_e64 s[2:3], v18, v193
	s_and_b64 vcc, vcc, s[2:3]
	v_add_u32_e32 v18, 48, v0
	v_cndmask_b32_e32 v9, v185, v9, vcc
	v_cmp_le_i32_e32 vcc, v18, v193
	v_add_u32_e32 v18, 0x230, v0
	v_cmp_gt_i32_e64 s[2:3], v18, v193
	s_and_b64 vcc, vcc, s[2:3]
	v_add_u32_e32 v18, 49, v0
	v_cndmask_b32_e32 v10, v185, v10, vcc
	v_cmp_le_i32_e32 vcc, v18, v193
	v_add_u32_e32 v18, 0x231, v0
	v_cmp_gt_i32_e64 s[2:3], v18, v193
	s_and_b64 vcc, vcc, s[2:3]
	v_add_u32_e32 v18, 50, v0
	v_cndmask_b32_e32 v11, v185, v11, vcc
	v_cmp_le_i32_e32 vcc, v18, v193
	v_add_u32_e32 v18, 0x232, v0
	v_cmp_gt_i32_e64 s[2:3], v18, v193
	s_and_b64 vcc, vcc, s[2:3]
	v_add_u32_e32 v18, 51, v0
	v_cndmask_b32_e32 v12, v185, v12, vcc
	v_cmp_le_i32_e32 vcc, v18, v193
	v_add_u32_e32 v18, 0x233, v0
	v_cmp_gt_i32_e64 s[2:3], v18, v193
	s_and_b64 vcc, vcc, s[2:3]
	v_add_u32_e32 v18, 56, v0
	v_cndmask_b32_e32 v13, v185, v13, vcc
	v_cmp_le_i32_e32 vcc, v18, v193
	v_add_u32_e32 v18, 0x238, v0
	v_cmp_gt_i32_e64 s[2:3], v18, v193
	s_and_b64 vcc, vcc, s[2:3]
	v_add_u32_e32 v18, 57, v0
	v_cndmask_b32_e32 v14, v185, v14, vcc
	v_cmp_le_i32_e32 vcc, v18, v193
	v_add_u32_e32 v18, 0x239, v0
	v_cmp_gt_i32_e64 s[2:3], v18, v193
	s_and_b64 vcc, vcc, s[2:3]
	v_add_u32_e32 v18, 58, v0
	v_cndmask_b32_e32 v15, v185, v15, vcc
	v_cmp_le_i32_e32 vcc, v18, v193
	v_add_u32_e32 v18, 0x23a, v0
	v_cmp_gt_i32_e64 s[2:3], v18, v193
	s_and_b64 vcc, vcc, s[2:3]
	v_add_u32_e32 v18, 59, v0
	v_add_u32_e32 v0, 0x23b, v0
	v_cndmask_b32_e32 v16, v185, v16, vcc
	v_cmp_le_i32_e32 vcc, v18, v193
	v_cmp_gt_i32_e64 s[2:3], v0, v193
	s_and_b64 vcc, vcc, s[2:3]
	v_cndmask_b32_e32 v17, v185, v17, vcc
.LBB0_4408:
	s_nop 8
	v_max3_f32 v0, v128, s66, v129
	v_max3_f32 v0, v0, v130, v131
	v_max3_f32 v0, v0, v132, v133
	v_max3_f32 v0, v0, v134, v135
	v_max3_f32 v0, v0, v136, v137
	v_max3_f32 v0, v0, v138, v139
	v_max3_f32 v0, v0, v140, v141
	v_max3_f32 v0, v0, v142, v143
	v_max3_f32 v0, v0, v2, v3
	v_max3_f32 v0, v0, v4, v5
	v_max3_f32 v0, v0, v6, v7
	v_max3_f32 v0, v0, v8, v9
	v_max3_f32 v0, v0, v10, v11
	v_max3_f32 v0, v0, v12, v13
	v_max3_f32 v0, v0, v14, v15
	v_max3_f32 v0, v0, v16, v17
	ds_bpermute_b32 v18, v175, v0
	s_waitcnt lgkmcnt(0)
	v_max_f32_e32 v18, v18, v18
	v_max_f32_e32 v0, v0, v18
	v_add_f32_e32 v18, 0x41000000, v229
	v_cmp_gt_f32_e32 vcc, v0, v18
	s_cbranch_vccz .LBB0_4403
	v_max_f32_e32 v0, v0, v0
	v_max_f32_e32 v230, v229, v229
	v_max_f32_e32 v230, v230, v0
	v_sub_f32_e32 v231, v230, v228
	v_sub_f32_e32 v0, v229, v230
	v_exp_f32_e32 v0, v0
	s_nop 0
	v_pk_mul_f32 v[126:127], v[126:127], v[0:1] op_sel_hi:[1,0]
	v_pk_mul_f32 v[124:125], v[124:125], v[0:1] op_sel_hi:[1,0]
	v_pk_mul_f32 v[122:123], v[122:123], v[0:1] op_sel_hi:[1,0]
	v_pk_mul_f32 v[120:121], v[120:121], v[0:1] op_sel_hi:[1,0]
	v_pk_mul_f32 v[118:119], v[118:119], v[0:1] op_sel_hi:[1,0]
	v_pk_mul_f32 v[116:117], v[116:117], v[0:1] op_sel_hi:[1,0]
	v_pk_mul_f32 v[114:115], v[114:115], v[0:1] op_sel_hi:[1,0]
	v_pk_mul_f32 v[112:113], v[112:113], v[0:1] op_sel_hi:[1,0]
	v_pk_mul_f32 v[110:111], v[110:111], v[0:1] op_sel_hi:[1,0]
	v_pk_mul_f32 v[108:109], v[108:109], v[0:1] op_sel_hi:[1,0]
	v_pk_mul_f32 v[106:107], v[106:107], v[0:1] op_sel_hi:[1,0]
	v_pk_mul_f32 v[104:105], v[104:105], v[0:1] op_sel_hi:[1,0]
	v_pk_mul_f32 v[102:103], v[102:103], v[0:1] op_sel_hi:[1,0]
	v_pk_mul_f32 v[100:101], v[100:101], v[0:1] op_sel_hi:[1,0]
	v_pk_mul_f32 v[98:99], v[98:99], v[0:1] op_sel_hi:[1,0]
	v_pk_mul_f32 v[96:97], v[96:97], v[0:1] op_sel_hi:[1,0]
	v_mul_f32_e32 v192, v192, v0
	v_mov_b32_e32 v200, v231
	v_xor_b32_e32 v230, 0x80000000, v231
	v_cmp_lt_f32_e32 vcc, 0xf0a18f08, v231
	s_nop 1
	v_cndmask_b32_e32 v230, 0, v230, vcc
	v_add_f32_e32 v229, v231, v230
	v_sub_f32_e32 v231, v230, v228
	v_mov_b32_e32 v228, v230
	v_add_f32_e32 v2, v231, v2
	v_add_f32_e32 v3, v231, v3
	v_add_f32_e32 v4, v231, v4
	v_add_f32_e32 v5, v231, v5
	v_add_f32_e32 v6, v231, v6
	v_add_f32_e32 v7, v231, v7
	v_add_f32_e32 v8, v231, v8
	v_add_f32_e32 v9, v231, v9
	v_add_f32_e32 v10, v231, v10
	v_add_f32_e32 v11, v231, v11
	v_add_f32_e32 v12, v231, v12
	v_add_f32_e32 v13, v231, v13
	v_add_f32_e32 v14, v231, v14
	v_add_f32_e32 v15, v231, v15
	v_add_f32_e32 v16, v231, v16
	v_add_f32_e32 v17, v231, v17
	v_add_f32_e32 v128, v231, v128
	v_add_f32_e32 v129, v231, v129
	v_add_f32_e32 v130, v231, v130
	v_add_f32_e32 v131, v231, v131
	v_add_f32_e32 v132, v231, v132
	v_add_f32_e32 v133, v231, v133
	v_add_f32_e32 v134, v231, v134
	v_add_f32_e32 v135, v231, v135
	v_add_f32_e32 v136, v231, v136
	v_add_f32_e32 v137, v231, v137
	v_add_f32_e32 v138, v231, v138
	v_add_f32_e32 v139, v231, v139
	v_add_f32_e32 v140, v231, v140
	v_add_f32_e32 v141, v231, v141
	v_add_f32_e32 v142, v231, v142
	v_add_f32_e32 v143, v231, v143
	v_mov_b32_e32 v212, v230
	v_mov_b32_e32 v213, v230
	v_mov_b32_e32 v214, v230
	v_mov_b32_e32 v215, v230
	v_mov_b32_e32 v216, v230
	v_mov_b32_e32 v217, v230
	v_mov_b32_e32 v218, v230
	v_mov_b32_e32 v219, v230
	v_mov_b32_e32 v220, v230
	v_mov_b32_e32 v221, v230
	v_mov_b32_e32 v222, v230
	v_mov_b32_e32 v223, v230
	v_mov_b32_e32 v224, v230
	v_mov_b32_e32 v225, v230
	v_mov_b32_e32 v226, v230
	v_mov_b32_e32 v227, v230
	s_branch .LBB0_4403
